# MoBA far tiles: S MFMA starts from per-lane constant tuple (c31 - m or -inf), exp without the 32 subtractions; tuple rebuilt per block / on rescale
# baseline (speedup 1.0000x reference)
; __device__ __forceinline__ int tid_opaque() { int t = threadIdx.x; asm volatile("" : "+v"(t)); return t; }
; __device__ __forceinline__ void phase_moba_mfma(const Params& p, LAS unsigned char* lds, unsigned lds_base) {
;     ...
;     const int tid = tid_opaque(), lane = tid & 63, wave = __builtin_amdgcn_readfirstlane(tid >> 6);
;     const int i32 = lane & 31, hh = lane >> 5;
;     bf16_t* MBQ = (bf16_t*)(p.ws + WS_MB); const bf16_t* MBK = MBQ + (size_t)M_ * D_; const bf16_t* MBV = MBK + (size_t)M_ * D_;
;     const float* KM = (const float*)(p.ws + WS_KMEAN); const float* BT = (const float*)(p.ws + WS_BT);
;     const int G = gridDim.x, cblk = blockIdx.x;
;     const int lrow = tid >> 3, lc = tid & 7;
;     const unsigned vbase = lds_base + OFF_V + (4 * hh + ((lane & 15) >> 2)) * VST + (16 * ((lane >> 4) & 1) + 4 * (lane & 3)) * 2;
;     const float NINF = -__builtin_inff();
;     for (int k = 0;; ++k) {
;         const int it = k * G + ((k & 1) ? (G - 1 - cblk) : cblk);
;         if (it >= 1024) break;
.LBB0_732:
	s_add_u32 s22, s26, 0x1e408000
	s_addc_u32 s23, s27, 0
	s_add_u32 s34, s26, 0x22408000
	s_addc_u32 s35, s27, 0
	v_readlane_b32 s65, v253, 5
	v_mov_b32_e32 v179, v247
	s_cmpk_gt_i32 s65, 0x3ff
	s_waitcnt lgkmcnt(0)
	s_barrier
	s_nop 0
	v_readfirstlane_b32 s0, v179
	s_cbranch_scc1 .LBB0_763
	s_waitcnt vmcnt(10)
	v_mbcnt_hi_u32_b32 v11, -1, v252
	s_waitcnt vmcnt(9)
	v_and_b32_e32 v13, 64, v11
	v_and_b32_e32 v1, 63, v179
	v_xor_b32_e32 v12, 32, v11
	v_add_u32_e32 v13, 64, v13
	v_cmp_lt_i32_e32 vcc, v12, v13
	v_cmp_eq_u32_e64 s[4:5], 0, v1
	v_cmp_gt_u32_e64 s[38:39], 32, v1
	v_xor_b32_e32 v1, 1, v11
	v_cndmask_b32_e32 v12, v11, v12, vcc
	v_cmp_lt_i32_e32 vcc, v1, v13
	s_not_b32 s1, s65
	s_add_i32 s1, s28, s1
	v_cndmask_b32_e32 v1, v11, v1, vcc
	v_lshlrev_b32_e32 v210, 2, v1
	v_xor_b32_e32 v1, 2, v11
	v_cmp_lt_i32_e32 vcc, v1, v13
	v_lshlrev_b32_e32 v5, 2, v179
	v_and_b32_e32 v0, 16, v179
	v_cndmask_b32_e32 v1, v11, v1, vcc
	v_lshlrev_b32_e32 v211, 2, v1
	v_xor_b32_e32 v1, 4, v11
	v_bfe_u32 v4, v179, 5, 1
	s_add_u32 s8, s26, 0xa348000
	v_and_or_b32 v0, v5, 12, v0
	v_cmp_lt_i32_e32 vcc, v1, v13
	v_lshlrev_b32_e32 v180, 2, v4
	s_addc_u32 s9, s27, 0
	v_lshlrev_b32_e32 v6, 1, v0
	v_lshrrev_b32_e32 v0, 2, v179
	s_ashr_i32 s0, s0, 6
	v_cndmask_b32_e32 v1, v11, v1, vcc
	v_writelane_b32 v255, s1, 5
	v_and_or_b32 v0, v0, 3, v180
	v_and_b32_e32 v8, 7, v179
	v_ashrrev_i32_e32 v182, 3, v179
	s_movk_i32 s1, 0x110
	s_lshl_b32 s18, s0, 5
	s_lshl_b32 s0, s0, 2
	v_lshlrev_b32_e32 v212, 2, v1
	v_xor_b32_e32 v1, 8, v11
	v_mul_u32_u24_e32 v7, 0x140, v0
	v_and_b32_e32 v9, 0x7c, v5
	v_mov_b32_e32 v0, 0
	s_add_i32 s2, 16, 0x12800
	v_lshlrev_b32_e32 v193, 2, v12
	v_writelane_b32 v255, s4, 6
	s_add_i32 s0, s0, 16
	v_lshlrev_b32_e32 v190, 4, v8
	v_mul_lo_u32 v12, v182, s1
	v_lshlrev_b32_e32 v8, 5, v8
	v_cmp_lt_i32_e32 vcc, v1, v13
	v_and_b32_e32 v178, 31, v179
	v_ashrrev_i32_e32 v181, 5, v179
	v_lshlrev_b32_e32 v2, 2, v9
	v_mov_b32_e32 v3, v0
	s_add_i32 s3, 16, 0x14a00
	v_mov_b32_e32 v10, s2
	v_writelane_b32 v255, s5, 7
	s_add_i32 s0, s0, 0x15a00
	v_add3_u32 v192, 16, v12, v8
	s_or_b32 s33, s18, 31
	v_cndmask_b32_e32 v1, v11, v1, vcc
	v_lshl_add_u64 v[188:189], s[72:73], 0, v[2:3]
	v_mul_lo_u32 v2, v181, s1
	v_mad_u32_u24 v10, v178, s1, v10
	v_writelane_b32 v255, s0, 8
	v_mad_u64_u32 v[194:195], s[0:1], v182, 48, v[192:193]
	s_cmp_lg_u32 16, -1
	v_lshlrev_b32_e32 v213, 2, v1
	v_xor_b32_e32 v1, 16, v11
	s_cselect_b32 s0, 16, 0
	v_cmp_lt_i32_e32 vcc, v1, v13
	v_add_u32_e32 v3, s2, v2
	v_lshlrev_b32_e32 v9, 1, v9
	v_add_u32_e32 v191, s3, v5
	v_lshlrev_b32_e32 v2, 3, v4
	v_mul_u32_u24_e32 v5, 0x110, v178
	v_lshlrev_b32_e32 v4, 4, v4
	s_add_i32 s0, s0, 0x8800
	v_cndmask_b32_e32 v1, v11, v1, vcc
	s_mov_b32 s2, s65
	s_mov_b32 s69, 0
	v_ashrrev_i32_e32 v183, 31, v182
	v_add3_u32 v195, 16, v5, v4
	v_add3_u32 v207, v6, s0, v7
	v_lshlrev_b32_e32 v214, 2, v1
	v_add_u32_e32 v215, v3, v9
	v_mov_b32_e32 v196, 0
	v_mov_b32_e32 v197, v0
	v_lshlrev_b32_e32 v198, 1, v2
	v_mov_b32_e32 v199, v0
	v_add_u32_e32 v216, v10, v4
	s_mov_b32 s29, 0xff800000
	v_mov_b32_e32 v217, 0xff800000
	s_add_i32 s20, 16, 0x15a10
	v_lshlrev_b32_e32 v200, 1, v180
	s_mov_b32 s21, 0
	v_and_b32_e32 v162, 63, v179
	v_lshrrev_b32_e32 v163, 6, v179
	v_lshrrev_b32_e32 v164, 4, v162
	v_and_b32_e32 v165, 15, v162
	v_lshl_add_u32 v166, v163, 3, v164
	v_and_b32_e32 v167, 15, v166
	v_xor_b32_e32 v167, v165, v167
	v_lshlrev_b32_e32 v167, 4, v167
	v_lshl_add_u32 v224, v166, 12, v167
	v_add_u32_e32 v168, 4, v166
	v_and_b32_e32 v167, 15, v168
	v_xor_b32_e32 v167, v165, v167
	v_lshlrev_b32_e32 v167, 4, v167
	v_lshl_add_u32 v225, v168, 12, v167
	v_lshlrev_b32_e32 v167, 2, v164
	v_xor_b32_e32 v167, v165, v167
	v_lshlrev_b32_e32 v167, 4, v167
	v_lshl_add_u32 v226, v166, 12, v167
	v_lshl_add_u32 v227, v168, 12, v167
	v_and_b32_e32 v166, 31, v162
	v_lshrrev_b32_e32 v167, 5, v162
	v_and_b32_e32 v168, 1, v166
	v_xor_b32_e32 v168, v167, v168
	v_lshlrev_b32_e32 v168, 4, v168
	v_bfe_u32 v169, v166, 1, 3
	v_lshl_or_b32 v168, v169, 5, v168
	v_lshl_or_b32 v175, v166, 8, v168
	v_bfe_u32 v166, v162, 2, 2
	v_bfe_u32 v168, v162, 4, 1
	v_and_b32_e32 v169, 3, v162
	v_lshl_add_u32 v163, v167, 2, v166
	v_lshlrev_b32_e32 v163, 8, v163
	v_lshl_or_b32 v163, v166, 6, v163
	v_lshl_or_b32 v163, v168, 5, v163
	v_lshl_or_b32 v176, v169, 3, v163
	s_branch .LBB0_735

; #define LAS __attribute__((address_space(3)))
; __device__ __forceinline__ void phase_moba_mfma(const Params& p, LAS unsigned char* lds, unsigned lds_base) {
;     ...
;                 const LAS unsigned char* Ks = lds + OFF_K + buf * 64 * KST + i32 * KST + 16 * hh;
;                 f32x16 s0, s1;
; #pragma unroll
;                 for (int r = 0; r < 16; ++r) { s0[r] = 0.f; s1[r] = 0.f; }
; #pragma unroll
;                 for (int kc = 0; kc < 8; ++kc) { const bf16x8 a0 = *(const LAS bf16x8*)(Ks + 32 * kc), a1 = *(const LAS bf16x8*)(Ks + 32 * KST + 32 * kc);
;                     s0 = MFMA32(a0, qf[kc], s0); s1 = MFMA32(a1, qf[kc], s1); }
;                 const int tq = q0 + i32, kbase = j * 256 + kt * 64;
;                 const bool far = (q0 - (kbase + 63)) >= 790;
;                 const bool diag = own && (kbase + 63 > q0);
;                 const bool lsel = own || ((sel >> j) & 1u);
;                 const int db = tq - kbase - 4 * hh;
;                 if (far) {
; #pragma unroll
;                     for (int r = 0; r < 16; ++r) { s0[r] += c31; s1[r] += c31; }
;                 } else {
;                     const LAS float* bp = (const LAS float*)(lds + OFF_BT) + db;
;                     float b0[16], b1[16];
; #pragma unroll
;                     for (int r = 0; r < 16; ++r) { b0[r] = bp[-(8 * (r >> 2) + (r & 3))]; b1[r] = bp[-(32 + 8 * (r >> 2) + (r & 3))]; }
; #pragma unroll
;                     for (int r = 0; r < 16; ++r) { s0[r] += b0[r]; s1[r] += b1[r]; }
;                 }
;     ...
;                 const unsigned va = vbase + buf * 64 * VST;
;                 u32x2 v[8];
;                 { const bf16x8 pf = pack8(s0, 0); tr8<0, 8 * VST, 64>(va, v);
; #pragma unroll
;                   for (int dt = 0; dt < 4; ++dt) O[dt] = MFMA32(frag2(v[2 * dt], v[2 * dt + 1]), pf, O[dt]); }
;                 { const bf16x8 pf = pack8(s0, 1); tr8<16 * VST, 8 * VST, 64>(va, v);
; #pragma unroll
;                   for (int dt = 0; dt < 4; ++dt) O[dt] = MFMA32(frag2(v[2 * dt], v[2 * dt + 1]), pf, O[dt]); }
;                 { const bf16x8 pf = pack8(s1, 0); tr8<32 * VST, 8 * VST, 64>(va, v);
; #pragma unroll
;                   for (int dt = 0; dt < 4; ++dt) O[dt] = MFMA32(frag2(v[2 * dt], v[2 * dt + 1]), pf, O[dt]); }
;                 { const bf16x8 pf = pack8(s1, 1); tr8<48 * VST, 8 * VST, 64>(va, v);
; #pragma unroll
.LBB0_747:
	s_cmp_lt_u32 s18, 0x80
	s_cbranch_scc1 .Lmoba_bodyA
	s_bitcmp0_b32 s2, 0
	s_cbranch_scc1 .Lmoba_bodyB
	s_add_i32 s0, s100, 3
	s_and_b32 s0, s0, 3
	s_mov_b32 s45, 0
	s_branch .Lmoba_pvblk
.Lmoba_pvblk:
	s_lshl_b32 s5, s0, 14
	s_add_i32 s5, s5, 0x12000
	s_cmp_eq_u32 s0, 0
	s_cselect_b32 s5, 0xc000, s5
	v_add_u32_e32 v170, s5, v176
	v_xor_b32_e32 v171, 0x40, v170
	v_xor_b32_e32 v172, 0x80, v170
	v_xor_b32_e32 v173, 0xc0, v170
	ds_read_b64_tr_b16 v[66:67], v170 offset:16
	ds_read_b64_tr_b16 v[68:69], v170 offset:2064
	ds_read_b64_tr_b16 v[70:71], v171 offset:16
	ds_read_b64_tr_b16 v[72:73], v171 offset:2064
	ds_read_b64_tr_b16 v[74:75], v172 offset:16
	ds_read_b64_tr_b16 v[76:77], v172 offset:2064
	ds_read_b64_tr_b16 v[78:79], v173 offset:16
	ds_read_b64_tr_b16 v[80:81], v173 offset:2064
	ds_read_b64_tr_b16 v[82:83], v170 offset:4112
	ds_read_b64_tr_b16 v[84:85], v170 offset:6160
	ds_read_b64_tr_b16 v[86:87], v171 offset:4112
	ds_read_b64_tr_b16 v[88:89], v171 offset:6160
	ds_read_b64_tr_b16 v[90:91], v172 offset:4112
	ds_read_b64_tr_b16 v[92:93], v172 offset:6160
	ds_read_b64_tr_b16 v[94:95], v173 offset:4112
	ds_read_b64_tr_b16 v[96:97], v173 offset:6160
	s_waitcnt lgkmcnt(8)
	v_mfma_f32_32x32x16_bf16 v[50:65], v[66:69], v[114:117], v[50:65]
	v_mfma_f32_32x32x16_bf16 v[34:49], v[70:73], v[114:117], v[34:49]
	v_mfma_f32_32x32x16_bf16 v[18:33], v[74:77], v[114:117], v[18:33]
	v_mfma_f32_32x32x16_bf16 v[2:17], v[78:81], v[114:117], v[2:17]
	ds_read_b64_tr_b16 v[66:67], v170 offset:8208
	ds_read_b64_tr_b16 v[68:69], v170 offset:10256
	ds_read_b64_tr_b16 v[70:71], v171 offset:8208
	ds_read_b64_tr_b16 v[72:73], v171 offset:10256
	ds_read_b64_tr_b16 v[74:75], v172 offset:8208
	ds_read_b64_tr_b16 v[76:77], v172 offset:10256
	ds_read_b64_tr_b16 v[78:79], v173 offset:8208
	ds_read_b64_tr_b16 v[80:81], v173 offset:10256
	s_waitcnt lgkmcnt(8)
	v_mfma_f32_32x32x16_bf16 v[50:65], v[82:85], v[118:121], v[50:65]
	v_mfma_f32_32x32x16_bf16 v[34:49], v[86:89], v[118:121], v[34:49]
	v_mfma_f32_32x32x16_bf16 v[18:33], v[90:93], v[118:121], v[18:33]
	v_mfma_f32_32x32x16_bf16 v[2:17], v[94:97], v[118:121], v[2:17]
	ds_read_b64_tr_b16 v[82:83], v170 offset:12304
	ds_read_b64_tr_b16 v[84:85], v170 offset:14352
	ds_read_b64_tr_b16 v[86:87], v171 offset:12304
	ds_read_b64_tr_b16 v[88:89], v171 offset:14352
	ds_read_b64_tr_b16 v[90:91], v172 offset:12304
	ds_read_b64_tr_b16 v[92:93], v172 offset:14352
	ds_read_b64_tr_b16 v[94:95], v173 offset:12304
	ds_read_b64_tr_b16 v[96:97], v173 offset:14352
	s_waitcnt lgkmcnt(8)
	v_mfma_f32_32x32x16_bf16 v[50:65], v[66:69], v[98:101], v[50:65]
	v_mfma_f32_32x32x16_bf16 v[34:49], v[70:73], v[98:101], v[34:49]
	v_mfma_f32_32x32x16_bf16 v[18:33], v[74:77], v[98:101], v[18:33]
	v_mfma_f32_32x32x16_bf16 v[2:17], v[78:81], v[98:101], v[2:17]
	s_waitcnt lgkmcnt(0)
	v_mfma_f32_32x32x16_bf16 v[50:65], v[82:85], v[102:105], v[50:65]
	v_mfma_f32_32x32x16_bf16 v[34:49], v[86:89], v[102:105], v[34:49]
	v_mfma_f32_32x32x16_bf16 v[18:33], v[90:93], v[102:105], v[18:33]
	v_mfma_f32_32x32x16_bf16 v[2:17], v[94:97], v[102:105], v[2:17]
	s_andn2_b32 s2, s2, 1
	s_cmp_eq_u32 s45, 0
	s_cbranch_scc1 .Lmoba_bodyB
	s_cmp_eq_u32 s45, 1
	s_cbranch_scc1 .Lmoba_ret1
	s_branch .LBB0_734
.Lmoba_bodyB:
	s_lshl_b32 s0, s19, 8
	s_lshl_b32 s1, s37, 6
	s_add_i32 s1, s1, s0
	s_or_b32 s4, s1, 63
	s_lshl_b32 s0, s101, 14
	v_add_u32_e32 v162, s0, v175
	v_xor_b32_e32 v163, 0x20, v162
	v_xor_b32_e32 v164, 0x40, v162
	v_xor_b32_e32 v165, 0x60, v162
	v_xor_b32_e32 v166, 0x80, v162
	v_xor_b32_e32 v167, 0xa0, v162
	v_xor_b32_e32 v168, 0xc0, v162
	v_xor_b32_e32 v169, 0xe0, v162
	s_sub_i32 s0, s6, s4
	s_cmpk_lt_i32 s0, 0x316
	s_cbranch_scc0 .Lmoba_farB
	v_or_b32_e32 v1, s1, v180
	v_sub_u32_e32 v1, v218, v1
	v_lshl_add_u32 v223, v1, 2, s3
	v_add_u32_e32 v223, 0xffffff14, v223
	ds_read2_b32 v[114:115], v223 offset0:59 offset1:58
	ds_read2_b32 v[98:99], v223 offset0:27 offset1:26
	ds_read2_b32 v[116:117], v223 offset0:57 offset1:56
	ds_read2_b32 v[100:101], v223 offset0:25 offset1:24
	ds_read2_b32 v[118:119], v223 offset0:51 offset1:50
	ds_read2_b32 v[102:103], v223 offset0:19 offset1:18
	ds_read2_b32 v[120:121], v223 offset0:49 offset1:48
	ds_read2_b32 v[104:105], v223 offset0:17 offset1:16
	ds_read2_b32 v[122:123], v223 offset0:43 offset1:42
	ds_read2_b32 v[106:107], v223 offset0:11 offset1:10
	ds_read2_b32 v[124:125], v223 offset0:41 offset1:40
	ds_read2_b32 v[108:109], v223 offset0:9 offset1:8
	ds_read2_b32 v[126:127], v223 offset0:35 offset1:34
	ds_read2_b32 v[110:111], v223 offset0:3 offset1:2
	ds_read2_b32 v[128:129], v223 offset0:33 offset1:32
	ds_read2_b32 v[112:113], v223 offset0:1 offset1:0
	ds_read_b128 v[66:69], v162 offset:16
	ds_read_b128 v[70:73], v162 offset:8208
	ds_read_b128 v[74:77], v163 offset:16
	ds_read_b128 v[78:81], v163 offset:8208
	ds_read_b128 v[82:85], v164 offset:16
	ds_read_b128 v[86:89], v164 offset:8208
	ds_read_b128 v[90:93], v165 offset:16
	ds_read_b128 v[94:97], v165 offset:8208
	s_waitcnt lgkmcnt(7)
	v_mfma_f32_32x32x16_bf16 v[114:129], v[66:69], v[130:133], v[114:129]
	ds_read_b128 v[66:69], v166 offset:16
	s_waitcnt lgkmcnt(7)
	v_mfma_f32_32x32x16_bf16 v[98:113], v[70:73], v[130:133], v[98:113]
	ds_read_b128 v[70:73], v166 offset:8208
	s_waitcnt lgkmcnt(7)
	v_mfma_f32_32x32x16_bf16 v[114:129], v[74:77], v[134:137], v[114:129]
	ds_read_b128 v[74:77], v167 offset:16
	s_waitcnt lgkmcnt(7)
	v_mfma_f32_32x32x16_bf16 v[98:113], v[78:81], v[134:137], v[98:113]
	ds_read_b128 v[78:81], v167 offset:8208
	s_waitcnt lgkmcnt(7)
	v_mfma_f32_32x32x16_bf16 v[114:129], v[82:85], v[138:141], v[114:129]
	ds_read_b128 v[82:85], v168 offset:16
	s_waitcnt lgkmcnt(7)
	v_mfma_f32_32x32x16_bf16 v[98:113], v[86:89], v[138:141], v[98:113]
	ds_read_b128 v[86:89], v168 offset:8208
	s_waitcnt lgkmcnt(7)
	v_mfma_f32_32x32x16_bf16 v[114:129], v[90:93], v[142:145], v[114:129]
	ds_read_b128 v[90:93], v169 offset:16
	s_waitcnt lgkmcnt(7)
	v_mfma_f32_32x32x16_bf16 v[98:113], v[94:97], v[142:145], v[98:113]
	ds_read_b128 v[94:97], v169 offset:8208
	s_waitcnt lgkmcnt(7)
	v_mfma_f32_32x32x16_bf16 v[114:129], v[66:69], v[146:149], v[114:129]
	s_waitcnt lgkmcnt(6)
	v_mfma_f32_32x32x16_bf16 v[98:113], v[70:73], v[146:149], v[98:113]
	s_waitcnt lgkmcnt(5)
	v_mfma_f32_32x32x16_bf16 v[114:129], v[74:77], v[150:153], v[114:129]
	s_waitcnt lgkmcnt(4)
	v_mfma_f32_32x32x16_bf16 v[98:113], v[78:81], v[150:153], v[98:113]
	s_waitcnt lgkmcnt(3)
	v_mfma_f32_32x32x16_bf16 v[114:129], v[82:85], v[154:157], v[114:129]
	s_waitcnt lgkmcnt(2)
	v_mfma_f32_32x32x16_bf16 v[98:113], v[86:89], v[154:157], v[98:113]
	s_waitcnt lgkmcnt(1)
	v_mfma_f32_32x32x16_bf16 v[114:129], v[90:93], v[158:161], v[114:129]
	s_waitcnt lgkmcnt(0)
	v_mfma_f32_32x32x16_bf16 v[98:113], v[94:97], v[158:161], v[98:113]
	s_nop 7
	s_cmp_ge_i32 s6, s4
	s_cselect_b64 s[0:1], -1, 0
	s_xor_b64 s[4:5], s[16:17], -1
	s_or_b64 s[0:1], s[4:5], s[0:1]
	s_and_b64 vcc, exec, s[0:1]
	s_cbranch_vccnz .Lmoba_nodiagB
; __device__ __forceinline__ void phase_moba_mfma(const Params& p, LAS unsigned char* lds, unsigned lds_base) {
;     ...
;                 if (diag) {
; #pragma unroll
;                     for (int r = 0; r < 16; ++r) { const int d0 = db - (8 * (r >> 2) + (r & 3)); if (d0 < 0) s0[r] = NINF; if (d0 < 32) s1[r] = NINF; }
;                 }
;                 float mx = NINF;
; #pragma unroll
;                 for (int r = 0; r < 16; ++r) { if (!lsel) { s0[r] = NINF; s1[r] = NINF; } mx = fmaxf(mx, fmaxf(s0[r], s1[r])); }
;                 mx = fmaxf(mx, __shfl_xor(mx, 32));
;                 const float mnew = fmaxf(m, mx);
;                 const float alpha = __builtin_amdgcn_exp2f(m - mnew);
;                 float ps = 0.f;
; #pragma unroll
;                 for (int r = 0; r < 16; ++r) { s0[r] = __builtin_amdgcn_exp2f(s0[r] - mnew); s1[r] = __builtin_amdgcn_exp2f(s1[r] - mnew); ps += s0[r] + s1[r]; }
;                 l = l * alpha + ps; m = mnew;
;                 if (__ballot(alpha != 1.0f) != 0ull) {
; #pragma unroll
;                     for (int dt = 0; dt < 4; ++dt)
; #pragma unroll
;                         for (int r = 0; r < 16; ++r) O[dt][r] *= alpha;
;                 }
	v_cmp_gt_i32_e64 s[4:5], 26, v1
	v_cmp_gt_i32_e32 vcc, 27, v1
	v_cmp_gt_i32_e64 s[96:97], 25, v1
	v_cmp_gt_i32_e64 s[94:95], 24, v1
	v_cndmask_b32_e32 v129, v129, v217, vcc
	s_and_b64 vcc, vcc, s[4:5]
	v_cndmask_b32_e32 v128, v128, v217, vcc
	s_and_b64 vcc, vcc, s[96:97]
	v_cmp_gt_i32_e64 s[92:93], 19, v1
	v_cndmask_b32_e32 v127, v127, v217, vcc
	s_and_b64 vcc, vcc, s[94:95]
	v_cmp_gt_i32_e64 s[90:91], 18, v1
	v_cndmask_b32_e32 v126, v126, v217, vcc
	s_and_b64 vcc, vcc, s[92:93]
	v_cmp_gt_i32_e64 s[88:89], 17, v1
	v_cndmask_b32_e32 v125, v125, v217, vcc
	s_and_b64 vcc, vcc, s[90:91]
	v_cmp_gt_i32_e64 s[86:87], 16, v1
	v_cndmask_b32_e32 v124, v124, v217, vcc
	s_and_b64 vcc, vcc, s[88:89]
	v_cmp_gt_i32_e64 s[84:85], 11, v1
	v_cndmask_b32_e32 v123, v123, v217, vcc
	s_and_b64 vcc, vcc, s[86:87]
	v_cmp_gt_i32_e64 s[82:83], 10, v1
	v_cndmask_b32_e32 v122, v122, v217, vcc
	s_and_b64 vcc, vcc, s[84:85]
	v_cmp_gt_i32_e64 s[80:81], 9, v1
	v_cndmask_b32_e32 v121, v121, v217, vcc
	s_and_b64 vcc, vcc, s[82:83]
	v_cmp_gt_i32_e64 s[78:79], 8, v1
	v_cndmask_b32_e32 v120, v120, v217, vcc
	s_and_b64 vcc, vcc, s[80:81]
	v_cmp_gt_i32_e64 s[76:77], 3, v1
	v_cndmask_b32_e32 v119, v119, v217, vcc
	s_and_b64 vcc, vcc, s[78:79]
	v_cmp_gt_i32_e64 s[74:75], 2, v1
	v_cndmask_b32_e32 v118, v118, v217, vcc
	s_and_b64 vcc, vcc, s[76:77]
	v_cmp_gt_i32_e64 s[72:73], 1, v1
	v_cndmask_b32_e32 v117, v117, v217, vcc
	s_and_b64 vcc, vcc, s[74:75]
	v_cmp_gt_i32_e64 s[66:67], 0, v1
	v_cndmask_b32_e32 v116, v116, v217, vcc
	s_and_b64 vcc, vcc, s[72:73]
	v_cndmask_b32_e32 v115, v115, v217, vcc
	s_and_b64 vcc, vcc, s[66:67]
	v_cmp_gt_i32_e64 s[64:65], 58, v1
	v_cndmask_b32_e32 v114, v114, v217, vcc
	v_cmp_gt_i32_e32 vcc, 59, v1
	v_cmp_gt_i32_e64 s[62:63], 57, v1
	v_cmp_gt_i32_e64 s[60:61], 56, v1
	v_cndmask_b32_e32 v113, v113, v217, vcc
	s_and_b64 vcc, vcc, s[64:65]
	v_cndmask_b32_e32 v112, v112, v217, vcc
	s_and_b64 vcc, vcc, s[62:63]
	v_cmp_gt_i32_e64 s[58:59], 51, v1
	v_cndmask_b32_e32 v111, v111, v217, vcc
	s_and_b64 vcc, vcc, s[60:61]
	v_cmp_gt_i32_e64 s[56:57], 50, v1
	v_cndmask_b32_e32 v110, v110, v217, vcc
	s_and_b64 vcc, vcc, s[58:59]
	v_cmp_gt_i32_e64 s[54:55], 49, v1
	v_cndmask_b32_e32 v109, v109, v217, vcc
	s_and_b64 vcc, vcc, s[56:57]
	v_cmp_gt_i32_e64 s[52:53], 48, v1
	v_cndmask_b32_e32 v108, v108, v217, vcc
	s_and_b64 vcc, vcc, s[54:55]
	v_cmp_gt_i32_e64 s[50:51], 43, v1
	v_cndmask_b32_e32 v107, v107, v217, vcc
	s_and_b64 vcc, vcc, s[52:53]
	v_cmp_gt_i32_e64 s[48:49], 42, v1
	v_cndmask_b32_e32 v106, v106, v217, vcc
	s_and_b64 vcc, vcc, s[50:51]
	v_cmp_gt_i32_e64 s[46:47], 41, v1
	v_cndmask_b32_e32 v105, v105, v217, vcc
	s_and_b64 vcc, vcc, s[48:49]
	v_cmp_gt_i32_e64 s[44:45], 40, v1
	v_cndmask_b32_e32 v104, v104, v217, vcc
	s_and_b64 vcc, vcc, s[46:47]
	v_cmp_gt_i32_e64 s[42:43], 35, v1
	v_cndmask_b32_e32 v103, v103, v217, vcc
	s_and_b64 vcc, vcc, s[44:45]
	v_cmp_gt_i32_e64 s[40:41], 34, v1
	v_cndmask_b32_e32 v102, v102, v217, vcc
	s_and_b64 vcc, vcc, s[42:43]
	v_cmp_gt_i32_e64 s[0:1], 33, v1
	v_cndmask_b32_e32 v101, v101, v217, vcc
	s_and_b64 vcc, vcc, s[40:41]
	v_cmp_gt_i32_e64 s[70:71], 32, v1
	v_cndmask_b32_e32 v100, v100, v217, vcc
	s_and_b64 vcc, vcc, s[0:1]
	v_cndmask_b32_e32 v99, v99, v217, vcc
	s_and_b64 vcc, vcc, s[70:71]
	v_cndmask_b32_e32 v98, v98, v217, vcc
.Lmoba_nodiagB:
	s_lshl_b32 s0, 1, s19
	v_and_b32_e32 v1, s0, v201
	v_cmp_ne_u32_e32 vcc, 0, v1
	s_or_b64 s[0:1], s[16:17], vcc
	v_max3_f32 v221, v114, v115, v116
	v_max3_f32 v222, v98, v99, v100
	v_max3_f32 v221, v221, v117, v118
	v_max3_f32 v222, v222, v101, v102
	v_max3_f32 v221, v221, v119, v120
	v_max3_f32 v222, v222, v103, v104
	v_max3_f32 v221, v221, v121, v122
	v_max3_f32 v222, v222, v105, v106
	v_max3_f32 v221, v221, v123, v124
	v_max3_f32 v222, v222, v107, v108
	v_max3_f32 v221, v221, v125, v126
	v_max3_f32 v222, v222, v109, v110
	v_max3_f32 v221, v221, v127, v128
	v_max3_f32 v222, v222, v111, v112
	v_max_f32_e32 v221, v221, v129
	v_max_f32_e32 v222, v222, v113
	v_max_f32_e32 v221, v221, v222
	v_cndmask_b32_e64 v221, v217, v221, s[0:1]
	v_mov_b32_e32 v223, v221
	v_mov_b32_e32 v248, 0x7f800000
	s_nop 1
	v_permlane32_swap_b32_e32 v223, v221
	v_max3_f32 v249, v220, v221, v223
	v_sub_f32_e32 v250, v249, v220
	v_cmp_lt_f32_e32 vcc, 0x41000000, v250
	s_nop 2
	v_cndmask_b32_e32 v1, v220, v249, vcc
	s_cbranch_vccz .Lmoba_norsB
	v_sub_f32_e32 v250, v220, v1
	v_exp_f32_e32 v244, v250
	s_and_b32 s2, s2, 0xff
	v_mul_f32_e32 v219, v219, v244
	v_pk_mul_f32 v[2:3], v[2:3], v[244:245] op_sel_hi:[1,0]
	v_pk_mul_f32 v[4:5], v[4:5], v[244:245] op_sel_hi:[1,0]
	v_pk_mul_f32 v[6:7], v[6:7], v[244:245] op_sel_hi:[1,0]
	v_pk_mul_f32 v[8:9], v[8:9], v[244:245] op_sel_hi:[1,0]
	v_pk_mul_f32 v[10:11], v[10:11], v[244:245] op_sel_hi:[1,0]
	v_pk_mul_f32 v[12:13], v[12:13], v[244:245] op_sel_hi:[1,0]
	v_pk_mul_f32 v[14:15], v[14:15], v[244:245] op_sel_hi:[1,0]
	v_pk_mul_f32 v[16:17], v[16:17], v[244:245] op_sel_hi:[1,0]
	v_pk_mul_f32 v[18:19], v[18:19], v[244:245] op_sel_hi:[1,0]
	v_pk_mul_f32 v[20:21], v[20:21], v[244:245] op_sel_hi:[1,0]
	v_pk_mul_f32 v[22:23], v[22:23], v[244:245] op_sel_hi:[1,0]
	v_pk_mul_f32 v[24:25], v[24:25], v[244:245] op_sel_hi:[1,0]
	v_pk_mul_f32 v[26:27], v[26:27], v[244:245] op_sel_hi:[1,0]
	v_pk_mul_f32 v[28:29], v[28:29], v[244:245] op_sel_hi:[1,0]
	v_pk_mul_f32 v[30:31], v[30:31], v[244:245] op_sel_hi:[1,0]
	v_pk_mul_f32 v[32:33], v[32:33], v[244:245] op_sel_hi:[1,0]
	v_pk_mul_f32 v[34:35], v[34:35], v[244:245] op_sel_hi:[1,0]
	v_pk_mul_f32 v[36:37], v[36:37], v[244:245] op_sel_hi:[1,0]
	v_pk_mul_f32 v[38:39], v[38:39], v[244:245] op_sel_hi:[1,0]
	v_pk_mul_f32 v[40:41], v[40:41], v[244:245] op_sel_hi:[1,0]
	v_pk_mul_f32 v[42:43], v[42:43], v[244:245] op_sel_hi:[1,0]
	v_pk_mul_f32 v[44:45], v[44:45], v[244:245] op_sel_hi:[1,0]
	v_pk_mul_f32 v[46:47], v[46:47], v[244:245] op_sel_hi:[1,0]
	v_pk_mul_f32 v[48:49], v[48:49], v[244:245] op_sel_hi:[1,0]
	v_pk_mul_f32 v[50:51], v[50:51], v[244:245] op_sel_hi:[1,0]
	v_pk_mul_f32 v[52:53], v[52:53], v[244:245] op_sel_hi:[1,0]
	v_pk_mul_f32 v[54:55], v[54:55], v[244:245] op_sel_hi:[1,0]
	v_pk_mul_f32 v[56:57], v[56:57], v[244:245] op_sel_hi:[1,0]
	v_pk_mul_f32 v[58:59], v[58:59], v[244:245] op_sel_hi:[1,0]
	v_pk_mul_f32 v[60:61], v[60:61], v[244:245] op_sel_hi:[1,0]
	v_pk_mul_f32 v[62:63], v[62:63], v[244:245] op_sel_hi:[1,0]
	v_pk_mul_f32 v[64:65], v[64:65], v[244:245] op_sel_hi:[1,0]
; __device__ __forceinline__ void phase_moba_mfma(const Params& p, LAS unsigned char* lds, unsigned lds_base) {
;     ...
;                 if (far) {
; #pragma unroll
;                     for (int r = 0; r < 16; ++r) { s0[r] += c31; s1[r] += c31; }
;     ...
;                 const float mnew = fmaxf(m, mx);
;                 const float alpha = __builtin_amdgcn_exp2f(m - mnew);
;                 float ps = 0.f;
; #pragma unroll
;                 for (int r = 0; r < 16; ++r) { s0[r] = __builtin_amdgcn_exp2f(s0[r] - mnew); s1[r] = __builtin_amdgcn_exp2f(s1[r] - mnew); ps += s0[r] + s1[r]; }
;                 l = l * alpha + ps; m = mnew;
.Lmoba_norsB:
	v_cndmask_b32_e64 v246, v248, v1, s[0:1]
	v_sub_f32_e32 v114, v114, v246
	v_sub_f32_e32 v115, v115, v246
	v_sub_f32_e32 v116, v116, v246
	v_sub_f32_e32 v117, v117, v246
	v_sub_f32_e32 v118, v118, v246
	v_sub_f32_e32 v119, v119, v246
	v_sub_f32_e32 v120, v120, v246
	v_sub_f32_e32 v121, v121, v246
	v_exp_f32_e32 v114, v114
	v_exp_f32_e32 v115, v115
	v_exp_f32_e32 v116, v116
	v_exp_f32_e32 v117, v117
	v_exp_f32_e32 v118, v118
	v_exp_f32_e32 v119, v119
	v_exp_f32_e32 v120, v120
	v_exp_f32_e32 v121, v121
	v_add_f32_e32 v244, v114, v115
	v_add_f32_e32 v245, v116, v117
	v_add_f32_e32 v244, v244, v118
	v_add_f32_e32 v245, v245, v119
	v_add_f32_e32 v244, v244, v120
	v_add_f32_e32 v245, v245, v121
	v_cvt_pk_bf16_f32 v114, v114, v115
	v_cvt_pk_bf16_f32 v115, v116, v117
	v_cvt_pk_bf16_f32 v116, v118, v119
	v_cvt_pk_bf16_f32 v117, v120, v121
	v_sub_f32_e32 v122, v122, v246
	v_sub_f32_e32 v123, v123, v246
	v_sub_f32_e32 v124, v124, v246
	v_sub_f32_e32 v125, v125, v246
	v_sub_f32_e32 v126, v126, v246
	v_sub_f32_e32 v127, v127, v246
	v_sub_f32_e32 v128, v128, v246
	v_sub_f32_e32 v129, v129, v246
	v_exp_f32_e32 v122, v122
	v_exp_f32_e32 v123, v123
	v_exp_f32_e32 v124, v124
	v_exp_f32_e32 v125, v125
	v_exp_f32_e32 v126, v126
	v_exp_f32_e32 v127, v127
	v_exp_f32_e32 v128, v128
	v_exp_f32_e32 v129, v129
	v_add_f32_e32 v244, v244, v122
	v_add_f32_e32 v245, v245, v123
	v_add_f32_e32 v244, v244, v124
	v_add_f32_e32 v245, v245, v125
	v_add_f32_e32 v244, v244, v126
	v_add_f32_e32 v245, v245, v127
	v_add_f32_e32 v244, v244, v128
	v_add_f32_e32 v245, v245, v129
	v_cvt_pk_bf16_f32 v118, v122, v123
	v_cvt_pk_bf16_f32 v119, v124, v125
	v_cvt_pk_bf16_f32 v120, v126, v127
	v_cvt_pk_bf16_f32 v121, v128, v129
	v_sub_f32_e32 v98, v98, v246
	v_sub_f32_e32 v99, v99, v246
	v_sub_f32_e32 v100, v100, v246
	v_sub_f32_e32 v101, v101, v246
	v_sub_f32_e32 v102, v102, v246
	v_sub_f32_e32 v103, v103, v246
	v_sub_f32_e32 v104, v104, v246
	v_sub_f32_e32 v105, v105, v246
	v_exp_f32_e32 v98, v98
	v_exp_f32_e32 v99, v99
	v_exp_f32_e32 v100, v100
	v_exp_f32_e32 v101, v101
	v_exp_f32_e32 v102, v102
	v_exp_f32_e32 v103, v103
	v_exp_f32_e32 v104, v104
	v_exp_f32_e32 v105, v105
	v_add_f32_e32 v244, v244, v98
	v_add_f32_e32 v245, v245, v99
	v_add_f32_e32 v244, v244, v100
	v_add_f32_e32 v245, v245, v101
	v_add_f32_e32 v244, v244, v102
	v_add_f32_e32 v245, v245, v103
	v_add_f32_e32 v244, v244, v104
	v_add_f32_e32 v245, v245, v105
	v_cvt_pk_bf16_f32 v98, v98, v99
	v_cvt_pk_bf16_f32 v99, v100, v101
	v_cvt_pk_bf16_f32 v100, v102, v103
	v_cvt_pk_bf16_f32 v101, v104, v105
	v_sub_f32_e32 v106, v106, v246
	v_sub_f32_e32 v107, v107, v246
	v_sub_f32_e32 v108, v108, v246
	v_sub_f32_e32 v109, v109, v246
	v_sub_f32_e32 v110, v110, v246
	v_sub_f32_e32 v111, v111, v246
	v_sub_f32_e32 v112, v112, v246
	v_sub_f32_e32 v113, v113, v246
	v_exp_f32_e32 v106, v106
	v_exp_f32_e32 v107, v107
	v_exp_f32_e32 v108, v108
	v_exp_f32_e32 v109, v109
	v_exp_f32_e32 v110, v110
	v_exp_f32_e32 v111, v111
	v_exp_f32_e32 v112, v112
	v_exp_f32_e32 v113, v113
	v_add_f32_e32 v244, v244, v106
	v_add_f32_e32 v245, v245, v107
	v_add_f32_e32 v244, v244, v108
	v_add_f32_e32 v245, v245, v109
	v_add_f32_e32 v244, v244, v110
	v_add_f32_e32 v245, v245, v111
	v_add_f32_e32 v244, v244, v112
	v_add_f32_e32 v245, v245, v113
	v_cvt_pk_bf16_f32 v102, v106, v107
	v_cvt_pk_bf16_f32 v103, v108, v109
	v_cvt_pk_bf16_f32 v104, v110, v111
	v_cvt_pk_bf16_f32 v105, v112, v113
	v_add_f32_e32 v244, v244, v245
	v_add_f32_e32 v219, v219, v244
	s_or_b32 s2, s2, 1
	s_branch .Lmoba_doneB
.Lmoba_farB:
	s_lshr_b32 s0, s2, 8
	s_add_i32 s1, s19, 1
	s_cmp_eq_u32 s0, s1
	s_cbranch_scc1 .Lmoba_tokB
	s_lshl_b32 s0, 1, s19
	v_and_b32_e32 v1, s0, v201
	v_cmp_ne_u32_e32 vcc, 0, v1
	v_sub_f32_e32 v223, v204, v220
	s_and_b32 s2, s2, 0xff
	s_lshl_b32 s1, s1, 8
	s_or_b32 s2, s2, s1
	v_cndmask_b32_e32 v228, v217, v223, vcc
	v_mov_b32_e32 v229, v228
	v_mov_b32_e32 v230, v228
	v_mov_b32_e32 v231, v228
	v_mov_b32_e32 v232, v228
	v_mov_b32_e32 v233, v228
	v_mov_b32_e32 v234, v228
	v_mov_b32_e32 v235, v228
	v_mov_b32_e32 v236, v228
	v_mov_b32_e32 v237, v228
	v_mov_b32_e32 v238, v228
	v_mov_b32_e32 v239, v228
	v_mov_b32_e32 v240, v228
	v_mov_b32_e32 v241, v228
	v_mov_b32_e32 v242, v228
	v_mov_b32_e32 v243, v228
; #define LAS __attribute__((address_space(3)))
; __device__ __forceinline__ void phase_moba_mfma(const Params& p, LAS unsigned char* lds, unsigned lds_base) {
;     ...
;                 for (int kc = 0; kc < 8; ++kc) { const bf16x8 a0 = *(const LAS bf16x8*)(Ks + 32 * kc), a1 = *(const LAS bf16x8*)(Ks + 32 * KST + 32 * kc);
;                     s0 = MFMA32(a0, qf[kc], s0); s1 = MFMA32(a1, qf[kc], s1); }
;                 const int tq = q0 + i32, kbase = j * 256 + kt * 64;
;                 const bool far = (q0 - (kbase + 63)) >= 790;
;                 const bool diag = own && (kbase + 63 > q0);
;                 const bool lsel = own || ((sel >> j) & 1u);
;                 const int db = tq - kbase - 4 * hh;
;                 if (far) {
; #pragma unroll
;                     for (int r = 0; r < 16; ++r) { s0[r] += c31; s1[r] += c31; }
;                 } else {
;                     const LAS float* bp = (const LAS float*)(lds + OFF_BT) + db;
;                     float b0[16], b1[16];
; #pragma unroll
;                     for (int r = 0; r < 16; ++r) { b0[r] = bp[-(8 * (r >> 2) + (r & 3))]; b1[r] = bp[-(32 + 8 * (r >> 2) + (r & 3))]; }
; #pragma unroll
;                     for (int r = 0; r < 16; ++r) { s0[r] += b0[r]; s1[r] += b1[r]; }
;                 }
;                 if (diag) {
; #pragma unroll
;                     for (int r = 0; r < 16; ++r) { const int d0 = db - (8 * (r >> 2) + (r & 3)); if (d0 < 0) s0[r] = NINF; if (d0 < 32) s1[r] = NINF; }
;                 }
;                 float mx = NINF;
; #pragma unroll
;                 for (int r = 0; r < 16; ++r) { if (!lsel) { s0[r] = NINF; s1[r] = NINF; } mx = fmaxf(mx, fmaxf(s0[r], s1[r])); }
;                 mx = fmaxf(mx, __shfl_xor(mx, 32));
;                 const float mnew = fmaxf(m, mx);
;                 const float alpha = __builtin_amdgcn_exp2f(m - mnew);
;                 float ps = 0.f;
; #pragma unroll
;                 for (int r = 0; r < 16; ++r) { s0[r] = __builtin_amdgcn_exp2f(s0[r] - mnew); s1[r] = __builtin_amdgcn_exp2f(s1[r] - mnew); ps += s0[r] + s1[r]; }
;                 l = l * alpha + ps; m = mnew;
;                 if (__ballot(alpha != 1.0f) != 0ull) {
; #pragma unroll
;                     for (int dt = 0; dt < 4; ++dt)
; #pragma unroll
;                         for (int r = 0; r < 16; ++r) O[dt][r] *= alpha;
.Lmoba_tokB:
	ds_read_b128 v[66:69], v162 offset:16
	ds_read_b128 v[70:73], v162 offset:8208
	ds_read_b128 v[74:77], v163 offset:16
	ds_read_b128 v[78:81], v163 offset:8208
	ds_read_b128 v[82:85], v164 offset:16
	ds_read_b128 v[86:89], v164 offset:8208
	ds_read_b128 v[90:93], v165 offset:16
	ds_read_b128 v[94:97], v165 offset:8208
	s_waitcnt lgkmcnt(7)
	v_mfma_f32_32x32x16_bf16 v[114:129], v[66:69], v[130:133], v[228:243]
	ds_read_b128 v[66:69], v166 offset:16
	s_waitcnt lgkmcnt(7)
	v_mfma_f32_32x32x16_bf16 v[98:113], v[70:73], v[130:133], v[228:243]
	ds_read_b128 v[70:73], v166 offset:8208
	s_waitcnt lgkmcnt(7)
	v_mfma_f32_32x32x16_bf16 v[114:129], v[74:77], v[134:137], v[114:129]
	ds_read_b128 v[74:77], v167 offset:16
	s_waitcnt lgkmcnt(7)
	v_mfma_f32_32x32x16_bf16 v[98:113], v[78:81], v[134:137], v[98:113]
	ds_read_b128 v[78:81], v167 offset:8208
	s_waitcnt lgkmcnt(7)
	v_mfma_f32_32x32x16_bf16 v[114:129], v[82:85], v[138:141], v[114:129]
	ds_read_b128 v[82:85], v168 offset:16
	s_waitcnt lgkmcnt(7)
	v_mfma_f32_32x32x16_bf16 v[98:113], v[86:89], v[138:141], v[98:113]
	ds_read_b128 v[86:89], v168 offset:8208
	s_waitcnt lgkmcnt(7)
	v_mfma_f32_32x32x16_bf16 v[114:129], v[90:93], v[142:145], v[114:129]
	ds_read_b128 v[90:93], v169 offset:16
	s_waitcnt lgkmcnt(7)
	v_mfma_f32_32x32x16_bf16 v[98:113], v[94:97], v[142:145], v[98:113]
	ds_read_b128 v[94:97], v169 offset:8208
	s_waitcnt lgkmcnt(7)
	v_mfma_f32_32x32x16_bf16 v[114:129], v[66:69], v[146:149], v[114:129]
	s_waitcnt lgkmcnt(6)
	v_mfma_f32_32x32x16_bf16 v[98:113], v[70:73], v[146:149], v[98:113]
	s_waitcnt lgkmcnt(5)
	v_mfma_f32_32x32x16_bf16 v[114:129], v[74:77], v[150:153], v[114:129]
	s_waitcnt lgkmcnt(4)
	v_mfma_f32_32x32x16_bf16 v[98:113], v[78:81], v[150:153], v[98:113]
	s_waitcnt lgkmcnt(3)
	v_mfma_f32_32x32x16_bf16 v[114:129], v[82:85], v[154:157], v[114:129]
	s_waitcnt lgkmcnt(2)
	v_mfma_f32_32x32x16_bf16 v[98:113], v[86:89], v[154:157], v[98:113]
	s_waitcnt lgkmcnt(1)
	v_mfma_f32_32x32x16_bf16 v[114:129], v[90:93], v[158:161], v[114:129]
	s_waitcnt lgkmcnt(0)
	v_mfma_f32_32x32x16_bf16 v[98:113], v[94:97], v[158:161], v[98:113]
	s_nop 7
	s_nop 3
	v_max3_f32 v221, v114, v115, v116
	v_max3_f32 v222, v98, v99, v100
	v_max3_f32 v221, v221, v117, v118
	v_max3_f32 v222, v222, v101, v102
	v_max3_f32 v221, v221, v119, v120
	v_max3_f32 v222, v222, v103, v104
	v_max3_f32 v221, v221, v121, v122
	v_max3_f32 v222, v222, v105, v106
	v_max3_f32 v221, v221, v123, v124
	v_max3_f32 v222, v222, v107, v108
	v_max3_f32 v221, v221, v125, v126
	v_max3_f32 v222, v222, v109, v110
	v_max3_f32 v221, v221, v127, v128
	v_max3_f32 v222, v222, v111, v112
	v_max_f32_e32 v221, v221, v129
	v_max_f32_e32 v222, v222, v113
	v_max_f32_e32 v221, v221, v222
	v_mov_b32_e32 v223, v221
	v_mov_b32_e32 v1, v220
	s_nop 1
	v_permlane32_swap_b32_e32 v223, v221
	v_max_f32_e32 v221, v221, v223
	v_cmp_lt_f32_e32 vcc, 0x41000000, v221
	s_cbranch_vccz .Lmoba_ffastB
	v_add_f32_e32 v249, v220, v221
	s_nop 0
	v_cndmask_b32_e32 v1, v220, v249, vcc
	v_sub_f32_e32 v250, v220, v1
	v_sub_f32_e32 v246, v1, v220
	v_exp_f32_e32 v244, v250
	s_and_b32 s2, s2, 0xff
	v_mul_f32_e32 v219, v219, v244
	v_pk_mul_f32 v[2:3], v[2:3], v[244:245] op_sel_hi:[1,0]
	v_pk_mul_f32 v[4:5], v[4:5], v[244:245] op_sel_hi:[1,0]
	v_pk_mul_f32 v[6:7], v[6:7], v[244:245] op_sel_hi:[1,0]
	v_pk_mul_f32 v[8:9], v[8:9], v[244:245] op_sel_hi:[1,0]
	v_pk_mul_f32 v[10:11], v[10:11], v[244:245] op_sel_hi:[1,0]
	v_pk_mul_f32 v[12:13], v[12:13], v[244:245] op_sel_hi:[1,0]
	v_pk_mul_f32 v[14:15], v[14:15], v[244:245] op_sel_hi:[1,0]
	v_pk_mul_f32 v[16:17], v[16:17], v[244:245] op_sel_hi:[1,0]
	v_pk_mul_f32 v[18:19], v[18:19], v[244:245] op_sel_hi:[1,0]
	v_pk_mul_f32 v[20:21], v[20:21], v[244:245] op_sel_hi:[1,0]
	v_pk_mul_f32 v[22:23], v[22:23], v[244:245] op_sel_hi:[1,0]
	v_pk_mul_f32 v[24:25], v[24:25], v[244:245] op_sel_hi:[1,0]
	v_pk_mul_f32 v[26:27], v[26:27], v[244:245] op_sel_hi:[1,0]
	v_pk_mul_f32 v[28:29], v[28:29], v[244:245] op_sel_hi:[1,0]
	v_pk_mul_f32 v[30:31], v[30:31], v[244:245] op_sel_hi:[1,0]
	v_pk_mul_f32 v[32:33], v[32:33], v[244:245] op_sel_hi:[1,0]
	v_pk_mul_f32 v[34:35], v[34:35], v[244:245] op_sel_hi:[1,0]
	v_pk_mul_f32 v[36:37], v[36:37], v[244:245] op_sel_hi:[1,0]
	v_pk_mul_f32 v[38:39], v[38:39], v[244:245] op_sel_hi:[1,0]
	v_pk_mul_f32 v[40:41], v[40:41], v[244:245] op_sel_hi:[1,0]
	v_pk_mul_f32 v[42:43], v[42:43], v[244:245] op_sel_hi:[1,0]
	v_pk_mul_f32 v[44:45], v[44:45], v[244:245] op_sel_hi:[1,0]
	v_pk_mul_f32 v[46:47], v[46:47], v[244:245] op_sel_hi:[1,0]
	v_pk_mul_f32 v[48:49], v[48:49], v[244:245] op_sel_hi:[1,0]
	v_pk_mul_f32 v[50:51], v[50:51], v[244:245] op_sel_hi:[1,0]
	v_pk_mul_f32 v[52:53], v[52:53], v[244:245] op_sel_hi:[1,0]
	v_pk_mul_f32 v[54:55], v[54:55], v[244:245] op_sel_hi:[1,0]
	v_pk_mul_f32 v[56:57], v[56:57], v[244:245] op_sel_hi:[1,0]
	v_pk_mul_f32 v[58:59], v[58:59], v[244:245] op_sel_hi:[1,0]
	v_pk_mul_f32 v[60:61], v[60:61], v[244:245] op_sel_hi:[1,0]
	v_pk_mul_f32 v[62:63], v[62:63], v[244:245] op_sel_hi:[1,0]
	v_pk_mul_f32 v[64:65], v[64:65], v[244:245] op_sel_hi:[1,0]
	v_sub_f32_e32 v114, v114, v246
	v_sub_f32_e32 v98, v98, v246
	v_sub_f32_e32 v115, v115, v246
	v_sub_f32_e32 v99, v99, v246
	v_sub_f32_e32 v116, v116, v246
	v_sub_f32_e32 v100, v100, v246
	v_sub_f32_e32 v117, v117, v246
	v_sub_f32_e32 v101, v101, v246
	v_sub_f32_e32 v118, v118, v246
	v_sub_f32_e32 v102, v102, v246
	v_sub_f32_e32 v119, v119, v246
	v_sub_f32_e32 v103, v103, v246
	v_sub_f32_e32 v120, v120, v246
	v_sub_f32_e32 v104, v104, v246
	v_sub_f32_e32 v121, v121, v246
	v_sub_f32_e32 v105, v105, v246
	v_sub_f32_e32 v122, v122, v246
	v_sub_f32_e32 v106, v106, v246
	v_sub_f32_e32 v123, v123, v246
	v_sub_f32_e32 v107, v107, v246
	v_sub_f32_e32 v124, v124, v246
	v_sub_f32_e32 v108, v108, v246
	v_sub_f32_e32 v125, v125, v246
	v_sub_f32_e32 v109, v109, v246
	v_sub_f32_e32 v126, v126, v246
	v_sub_f32_e32 v110, v110, v246
	v_sub_f32_e32 v127, v127, v246
	v_sub_f32_e32 v111, v111, v246
	v_sub_f32_e32 v128, v128, v246
	v_sub_f32_e32 v112, v112, v246
	v_sub_f32_e32 v129, v129, v246
	v_sub_f32_e32 v113, v113, v246
; #define LAS __attribute__((address_space(3)))
; #define MFMA32(a, b, c) __builtin_amdgcn_mfma_f32_32x32x16_bf16((a), (b), (c), 0, 0, 0)
; __device__ __forceinline__ void phase_moba_mfma(const Params& p, LAS unsigned char* lds, unsigned lds_base) {
;     ...
;                 const LAS unsigned char* Ks = lds + OFF_K + buf * 64 * KST + i32 * KST + 16 * hh;
;                 f32x16 s0, s1;
; #pragma unroll
;                 for (int r = 0; r < 16; ++r) { s0[r] = 0.f; s1[r] = 0.f; }
; #pragma unroll
;                 for (int kc = 0; kc < 8; ++kc) { const bf16x8 a0 = *(const LAS bf16x8*)(Ks + 32 * kc), a1 = *(const LAS bf16x8*)(Ks + 32 * KST + 32 * kc);
;                     s0 = MFMA32(a0, qf[kc], s0); s1 = MFMA32(a1, qf[kc], s1); }
;                 const int tq = q0 + i32, kbase = j * 256 + kt * 64;
;                 const bool far = (q0 - (kbase + 63)) >= 790;
;                 const bool diag = own && (kbase + 63 > q0);
;                 const bool lsel = own || ((sel >> j) & 1u);
;                 const int db = tq - kbase - 4 * hh;
;                 if (far) {
; #pragma unroll
;                     for (int r = 0; r < 16; ++r) { s0[r] += c31; s1[r] += c31; }
;                 } else {
;                     const LAS float* bp = (const LAS float*)(lds + OFF_BT) + db;
;     ...
;                 for (int r = 0; r < 16; ++r) { s0[r] = __builtin_amdgcn_exp2f(s0[r] - mnew); s1[r] = __builtin_amdgcn_exp2f(s1[r] - mnew); ps += s0[r] + s1[r]; }
;                 l = l * alpha + ps; m = mnew;
.Lmoba_ffastB:
	v_exp_f32_e32 v114, v114
	v_exp_f32_e32 v115, v115
	v_exp_f32_e32 v116, v116
	v_exp_f32_e32 v117, v117
	v_exp_f32_e32 v118, v118
	v_exp_f32_e32 v119, v119
	v_exp_f32_e32 v120, v120
	v_exp_f32_e32 v121, v121
	v_add_f32_e32 v244, v114, v115
	v_add_f32_e32 v245, v116, v117
	v_add_f32_e32 v244, v244, v118
	v_add_f32_e32 v245, v245, v119
	v_add_f32_e32 v244, v244, v120
	v_add_f32_e32 v245, v245, v121
	v_cvt_pk_bf16_f32 v114, v114, v115
	v_cvt_pk_bf16_f32 v115, v116, v117
	v_cvt_pk_bf16_f32 v116, v118, v119
	v_cvt_pk_bf16_f32 v117, v120, v121
	v_exp_f32_e32 v122, v122
	v_exp_f32_e32 v123, v123
	v_exp_f32_e32 v124, v124
	v_exp_f32_e32 v125, v125
	v_exp_f32_e32 v126, v126
	v_exp_f32_e32 v127, v127
	v_exp_f32_e32 v128, v128
	v_exp_f32_e32 v129, v129
	v_add_f32_e32 v244, v244, v122
	v_add_f32_e32 v245, v245, v123
	v_add_f32_e32 v244, v244, v124
	v_add_f32_e32 v245, v245, v125
	v_add_f32_e32 v244, v244, v126
	v_add_f32_e32 v245, v245, v127
	v_add_f32_e32 v244, v244, v128
	v_add_f32_e32 v245, v245, v129
	v_cvt_pk_bf16_f32 v118, v122, v123
	v_cvt_pk_bf16_f32 v119, v124, v125
	v_cvt_pk_bf16_f32 v120, v126, v127
	v_cvt_pk_bf16_f32 v121, v128, v129
	v_exp_f32_e32 v98, v98
	v_exp_f32_e32 v99, v99
	v_exp_f32_e32 v100, v100
	v_exp_f32_e32 v101, v101
	v_exp_f32_e32 v102, v102
	v_exp_f32_e32 v103, v103
	v_exp_f32_e32 v104, v104
	v_exp_f32_e32 v105, v105
	v_add_f32_e32 v244, v244, v98
	v_add_f32_e32 v245, v245, v99
	v_add_f32_e32 v244, v244, v100
	v_add_f32_e32 v245, v245, v101
	v_add_f32_e32 v244, v244, v102
	v_add_f32_e32 v245, v245, v103
	v_add_f32_e32 v244, v244, v104
	v_add_f32_e32 v245, v245, v105
	v_cvt_pk_bf16_f32 v98, v98, v99
	v_cvt_pk_bf16_f32 v99, v100, v101
	v_cvt_pk_bf16_f32 v100, v102, v103
	v_cvt_pk_bf16_f32 v101, v104, v105
	v_exp_f32_e32 v106, v106
	v_exp_f32_e32 v107, v107
	v_exp_f32_e32 v108, v108
	v_exp_f32_e32 v109, v109
	v_exp_f32_e32 v110, v110
	v_exp_f32_e32 v111, v111
	v_exp_f32_e32 v112, v112
	v_exp_f32_e32 v113, v113
	v_add_f32_e32 v244, v244, v106
	v_add_f32_e32 v245, v245, v107
	v_add_f32_e32 v244, v244, v108
	v_add_f32_e32 v245, v245, v109
	v_add_f32_e32 v244, v244, v110
	v_add_f32_e32 v245, v245, v111
	v_add_f32_e32 v244, v244, v112
	v_add_f32_e32 v245, v245, v113
	v_cvt_pk_bf16_f32 v102, v106, v107
	v_cvt_pk_bf16_f32 v103, v108, v109
	v_cvt_pk_bf16_f32 v104, v110, v111
	v_cvt_pk_bf16_f32 v105, v112, v113
	v_add_f32_e32 v244, v244, v245
	v_add_f32_e32 v219, v219, v244
	s_or_b32 s2, s2, 1
.Lmoba_doneB:
	s_branch .Lmoba_tail
.Lmoba_bodyA:
	s_lshl_b32 s0, s19, 8
	s_lshl_b32 s1, s37, 6
	s_add_i32 s1, s1, s0
	s_or_b32 s4, s1, 63
	s_lshl_b32 s0, s101, 14
	v_add_u32_e32 v162, s0, v175
	v_xor_b32_e32 v163, 0x20, v162
	v_xor_b32_e32 v164, 0x40, v162
	v_xor_b32_e32 v165, 0x60, v162
	v_xor_b32_e32 v166, 0x80, v162
	v_xor_b32_e32 v167, 0xa0, v162
	v_xor_b32_e32 v168, 0xc0, v162
	v_xor_b32_e32 v169, 0xe0, v162
	s_lshl_b32 s5, s100, 14
	s_add_i32 s5, s5, 0x12000
	s_cmp_eq_u32 s100, 0
	s_cselect_b32 s5, 0xc000, s5
	v_add_u32_e32 v170, s5, v176
	v_xor_b32_e32 v171, 0x40, v170
	v_xor_b32_e32 v172, 0x80, v170
	v_xor_b32_e32 v173, 0xc0, v170
	s_sub_i32 s0, s6, s4
	s_cmpk_lt_i32 s0, 0x316
	s_cbranch_scc0 .Lmoba_farA
	v_or_b32_e32 v1, s1, v180
	v_sub_u32_e32 v1, v218, v1
	v_lshl_add_u32 v223, v1, 2, s3
	v_add_u32_e32 v223, 0xffffff14, v223
	ds_read2_b32 v[114:115], v223 offset0:59 offset1:58
	ds_read2_b32 v[98:99], v223 offset0:27 offset1:26
	ds_read2_b32 v[116:117], v223 offset0:57 offset1:56
	ds_read2_b32 v[100:101], v223 offset0:25 offset1:24
	ds_read2_b32 v[118:119], v223 offset0:51 offset1:50
	ds_read2_b32 v[102:103], v223 offset0:19 offset1:18
	ds_read2_b32 v[120:121], v223 offset0:49 offset1:48
	ds_read2_b32 v[104:105], v223 offset0:17 offset1:16
	ds_read2_b32 v[122:123], v223 offset0:43 offset1:42
	ds_read2_b32 v[106:107], v223 offset0:11 offset1:10
	ds_read2_b32 v[124:125], v223 offset0:41 offset1:40
	ds_read2_b32 v[108:109], v223 offset0:9 offset1:8
	ds_read2_b32 v[126:127], v223 offset0:35 offset1:34
	ds_read2_b32 v[110:111], v223 offset0:3 offset1:2
	ds_read2_b32 v[128:129], v223 offset0:33 offset1:32
	ds_read2_b32 v[112:113], v223 offset0:1 offset1:0
	ds_read_b128 v[66:69], v162 offset:16
	ds_read_b128 v[70:73], v162 offset:8208
	ds_read_b128 v[74:77], v163 offset:16
	ds_read_b128 v[78:81], v163 offset:8208
	ds_read_b128 v[82:85], v164 offset:16
	ds_read_b128 v[86:89], v164 offset:8208
	ds_read_b128 v[90:93], v165 offset:16
	ds_read_b128 v[94:97], v165 offset:8208
	s_waitcnt lgkmcnt(7)
	v_mfma_f32_32x32x16_bf16 v[114:129], v[66:69], v[130:133], v[114:129]
	ds_read_b128 v[66:69], v166 offset:16
	s_waitcnt lgkmcnt(7)
	v_mfma_f32_32x32x16_bf16 v[98:113], v[70:73], v[130:133], v[98:113]
	ds_read_b128 v[70:73], v166 offset:8208
	s_waitcnt lgkmcnt(7)
	v_mfma_f32_32x32x16_bf16 v[114:129], v[74:77], v[134:137], v[114:129]
	ds_read_b128 v[74:77], v167 offset:16
	s_waitcnt lgkmcnt(7)
	v_mfma_f32_32x32x16_bf16 v[98:113], v[78:81], v[134:137], v[98:113]
	ds_read_b128 v[78:81], v167 offset:8208
	s_waitcnt lgkmcnt(7)
	v_mfma_f32_32x32x16_bf16 v[114:129], v[82:85], v[138:141], v[114:129]
	ds_read_b128 v[82:85], v168 offset:16
	s_waitcnt lgkmcnt(7)
	v_mfma_f32_32x32x16_bf16 v[98:113], v[86:89], v[138:141], v[98:113]
	ds_read_b128 v[86:89], v168 offset:8208
	s_waitcnt lgkmcnt(7)
; #define LAS __attribute__((address_space(3)))
; #define MFMA32(a, b, c) __builtin_amdgcn_mfma_f32_32x32x16_bf16((a), (b), (c), 0, 0, 0)
; __device__ __forceinline__ void phase_moba_mfma(const Params& p, LAS unsigned char* lds, unsigned lds_base) {
;     ...
;                 for (int kc = 0; kc < 8; ++kc) { const bf16x8 a0 = *(const LAS bf16x8*)(Ks + 32 * kc), a1 = *(const LAS bf16x8*)(Ks + 32 * KST + 32 * kc);
;                     s0 = MFMA32(a0, qf[kc], s0); s1 = MFMA32(a1, qf[kc], s1); }
;                 const int tq = q0 + i32, kbase = j * 256 + kt * 64;
;                 const bool far = (q0 - (kbase + 63)) >= 790;
;                 const bool diag = own && (kbase + 63 > q0);
;                 const bool lsel = own || ((sel >> j) & 1u);
;                 const int db = tq - kbase - 4 * hh;
;                 if (far) {
; #pragma unroll
;                     for (int r = 0; r < 16; ++r) { s0[r] += c31; s1[r] += c31; }
;                 } else {
;                     const LAS float* bp = (const LAS float*)(lds + OFF_BT) + db;
;                     float b0[16], b1[16];
; #pragma unroll
;                     for (int r = 0; r < 16; ++r) { b0[r] = bp[-(8 * (r >> 2) + (r & 3))]; b1[r] = bp[-(32 + 8 * (r >> 2) + (r & 3))]; }
; #pragma unroll
;                     for (int r = 0; r < 16; ++r) { s0[r] += b0[r]; s1[r] += b1[r]; }
;                 }
;                 if (diag) {
; #pragma unroll
;                     for (int r = 0; r < 16; ++r) { const int d0 = db - (8 * (r >> 2) + (r & 3)); if (d0 < 0) s0[r] = NINF; if (d0 < 32) s1[r] = NINF; }
;                 }
	v_mfma_f32_32x32x16_bf16 v[114:129], v[90:93], v[142:145], v[114:129]
	ds_read_b128 v[90:93], v169 offset:16
	s_waitcnt lgkmcnt(7)
	v_mfma_f32_32x32x16_bf16 v[98:113], v[94:97], v[142:145], v[98:113]
	ds_read_b128 v[94:97], v169 offset:8208
	s_waitcnt lgkmcnt(7)
	v_mfma_f32_32x32x16_bf16 v[114:129], v[66:69], v[146:149], v[114:129]
	s_waitcnt lgkmcnt(6)
	v_mfma_f32_32x32x16_bf16 v[98:113], v[70:73], v[146:149], v[98:113]
	s_waitcnt lgkmcnt(5)
	v_mfma_f32_32x32x16_bf16 v[114:129], v[74:77], v[150:153], v[114:129]
	s_waitcnt lgkmcnt(4)
	v_mfma_f32_32x32x16_bf16 v[98:113], v[78:81], v[150:153], v[98:113]
	s_waitcnt lgkmcnt(3)
	v_mfma_f32_32x32x16_bf16 v[114:129], v[82:85], v[154:157], v[114:129]
	s_waitcnt lgkmcnt(2)
	v_mfma_f32_32x32x16_bf16 v[98:113], v[86:89], v[154:157], v[98:113]
	s_waitcnt lgkmcnt(1)
	v_mfma_f32_32x32x16_bf16 v[114:129], v[90:93], v[158:161], v[114:129]
	s_waitcnt lgkmcnt(0)
	v_mfma_f32_32x32x16_bf16 v[98:113], v[94:97], v[158:161], v[98:113]
	ds_read_b64_tr_b16 v[66:67], v170 offset:16
	ds_read_b64_tr_b16 v[68:69], v170 offset:2064
	ds_read_b64_tr_b16 v[70:71], v171 offset:16
	ds_read_b64_tr_b16 v[72:73], v171 offset:2064
	ds_read_b64_tr_b16 v[74:75], v172 offset:16
	ds_read_b64_tr_b16 v[76:77], v172 offset:2064
	ds_read_b64_tr_b16 v[78:79], v173 offset:16
	ds_read_b64_tr_b16 v[80:81], v173 offset:2064
	ds_read_b64_tr_b16 v[82:83], v170 offset:4112
	ds_read_b64_tr_b16 v[84:85], v170 offset:6160
	ds_read_b64_tr_b16 v[86:87], v171 offset:4112
	ds_read_b64_tr_b16 v[88:89], v171 offset:6160
	ds_read_b64_tr_b16 v[90:91], v172 offset:4112
	ds_read_b64_tr_b16 v[92:93], v172 offset:6160
	ds_read_b64_tr_b16 v[94:95], v173 offset:4112
	ds_read_b64_tr_b16 v[96:97], v173 offset:6160
	s_cmp_ge_i32 s6, s4
	s_cselect_b64 s[0:1], -1, 0
	s_xor_b64 s[4:5], s[16:17], -1
	s_or_b64 s[0:1], s[4:5], s[0:1]
	s_and_b64 vcc, exec, s[0:1]
	s_cbranch_vccnz .Lmoba_nodiagA
	v_cmp_gt_i32_e64 s[4:5], 26, v1
	v_cmp_gt_i32_e32 vcc, 27, v1
	v_cmp_gt_i32_e64 s[96:97], 25, v1
	v_cmp_gt_i32_e64 s[94:95], 24, v1
	v_cndmask_b32_e32 v129, v129, v217, vcc
	s_and_b64 vcc, vcc, s[4:5]
	v_cndmask_b32_e32 v128, v128, v217, vcc
	s_and_b64 vcc, vcc, s[96:97]
	v_cmp_gt_i32_e64 s[92:93], 19, v1
	v_cndmask_b32_e32 v127, v127, v217, vcc
	s_and_b64 vcc, vcc, s[94:95]
	v_cmp_gt_i32_e64 s[90:91], 18, v1
	v_cndmask_b32_e32 v126, v126, v217, vcc
	s_and_b64 vcc, vcc, s[92:93]
	v_cmp_gt_i32_e64 s[88:89], 17, v1
	v_cndmask_b32_e32 v125, v125, v217, vcc
	s_and_b64 vcc, vcc, s[90:91]
	v_cmp_gt_i32_e64 s[86:87], 16, v1
	v_cndmask_b32_e32 v124, v124, v217, vcc
	s_and_b64 vcc, vcc, s[88:89]
	v_cmp_gt_i32_e64 s[84:85], 11, v1
	v_cndmask_b32_e32 v123, v123, v217, vcc
	s_and_b64 vcc, vcc, s[86:87]
	v_cmp_gt_i32_e64 s[82:83], 10, v1
	v_cndmask_b32_e32 v122, v122, v217, vcc
	s_and_b64 vcc, vcc, s[84:85]
	v_cmp_gt_i32_e64 s[80:81], 9, v1
	v_cndmask_b32_e32 v121, v121, v217, vcc
	s_and_b64 vcc, vcc, s[82:83]
	v_cmp_gt_i32_e64 s[78:79], 8, v1
	v_cndmask_b32_e32 v120, v120, v217, vcc
	s_and_b64 vcc, vcc, s[80:81]
	v_cmp_gt_i32_e64 s[76:77], 3, v1
	v_cndmask_b32_e32 v119, v119, v217, vcc
	s_and_b64 vcc, vcc, s[78:79]
	v_cmp_gt_i32_e64 s[74:75], 2, v1
	v_cndmask_b32_e32 v118, v118, v217, vcc
	s_and_b64 vcc, vcc, s[76:77]
	v_cmp_gt_i32_e64 s[72:73], 1, v1
	v_cndmask_b32_e32 v117, v117, v217, vcc
	s_and_b64 vcc, vcc, s[74:75]
	v_cmp_gt_i32_e64 s[66:67], 0, v1
	v_cndmask_b32_e32 v116, v116, v217, vcc
	s_and_b64 vcc, vcc, s[72:73]
	v_cndmask_b32_e32 v115, v115, v217, vcc
	s_and_b64 vcc, vcc, s[66:67]
	v_cmp_gt_i32_e64 s[64:65], 58, v1
	v_cndmask_b32_e32 v114, v114, v217, vcc
	v_cmp_gt_i32_e32 vcc, 59, v1
	v_cmp_gt_i32_e64 s[62:63], 57, v1
	v_cmp_gt_i32_e64 s[60:61], 56, v1
	v_cndmask_b32_e32 v113, v113, v217, vcc
	s_and_b64 vcc, vcc, s[64:65]
	v_cndmask_b32_e32 v112, v112, v217, vcc
	s_and_b64 vcc, vcc, s[62:63]
	v_cmp_gt_i32_e64 s[58:59], 51, v1
	v_cndmask_b32_e32 v111, v111, v217, vcc
	s_and_b64 vcc, vcc, s[60:61]
	v_cmp_gt_i32_e64 s[56:57], 50, v1
	v_cndmask_b32_e32 v110, v110, v217, vcc
	s_and_b64 vcc, vcc, s[58:59]
	v_cmp_gt_i32_e64 s[54:55], 49, v1
	v_cndmask_b32_e32 v109, v109, v217, vcc
	s_and_b64 vcc, vcc, s[56:57]
	v_cmp_gt_i32_e64 s[52:53], 48, v1
	v_cndmask_b32_e32 v108, v108, v217, vcc
	s_and_b64 vcc, vcc, s[54:55]
	v_cmp_gt_i32_e64 s[50:51], 43, v1
	v_cndmask_b32_e32 v107, v107, v217, vcc
	s_and_b64 vcc, vcc, s[52:53]
	v_cmp_gt_i32_e64 s[48:49], 42, v1
	v_cndmask_b32_e32 v106, v106, v217, vcc
	s_and_b64 vcc, vcc, s[50:51]
	v_cmp_gt_i32_e64 s[46:47], 41, v1
	v_cndmask_b32_e32 v105, v105, v217, vcc
	s_and_b64 vcc, vcc, s[48:49]
	v_cmp_gt_i32_e64 s[44:45], 40, v1
	v_cndmask_b32_e32 v104, v104, v217, vcc
	s_and_b64 vcc, vcc, s[46:47]
	v_cmp_gt_i32_e64 s[42:43], 35, v1
	v_cndmask_b32_e32 v103, v103, v217, vcc
	s_and_b64 vcc, vcc, s[44:45]
	v_cmp_gt_i32_e64 s[40:41], 34, v1
	v_cndmask_b32_e32 v102, v102, v217, vcc
	s_and_b64 vcc, vcc, s[42:43]
	v_cmp_gt_i32_e64 s[0:1], 33, v1
	v_cndmask_b32_e32 v101, v101, v217, vcc
	s_and_b64 vcc, vcc, s[40:41]
	v_cmp_gt_i32_e64 s[70:71], 32, v1
	v_cndmask_b32_e32 v100, v100, v217, vcc
	s_and_b64 vcc, vcc, s[0:1]
	v_cndmask_b32_e32 v99, v99, v217, vcc
	s_and_b64 vcc, vcc, s[70:71]
	v_cndmask_b32_e32 v98, v98, v217, vcc

; #define MFMA32(a, b, c) __builtin_amdgcn_mfma_f32_32x32x16_bf16((a), (b), (c), 0, 0, 0)
; __device__ __forceinline__ void phase_moba_mfma(const Params& p, LAS unsigned char* lds, unsigned lds_base) {
;     ...
;                 const float mnew = fmaxf(m, mx);
;                 const float alpha = __builtin_amdgcn_exp2f(m - mnew);
;                 float ps = 0.f;
; #pragma unroll
;                 for (int r = 0; r < 16; ++r) { s0[r] = __builtin_amdgcn_exp2f(s0[r] - mnew); s1[r] = __builtin_amdgcn_exp2f(s1[r] - mnew); ps += s0[r] + s1[r]; }
;                 l = l * alpha + ps; m = mnew;
;                 if (__ballot(alpha != 1.0f) != 0ull) {
; #pragma unroll
;                     for (int dt = 0; dt < 4; ++dt)
; #pragma unroll
;                         for (int r = 0; r < 16; ++r) O[dt][r] *= alpha;
;                 }
;                 const unsigned va = vbase + buf * 64 * VST;
;                 u32x2 v[8];
;                 { const bf16x8 pf = pack8(s0, 0); tr8<0, 8 * VST, 64>(va, v);
; #pragma unroll
;                   for (int dt = 0; dt < 4; ++dt) O[dt] = MFMA32(frag2(v[2 * dt], v[2 * dt + 1]), pf, O[dt]); }
;                 { const bf16x8 pf = pack8(s0, 1); tr8<16 * VST, 8 * VST, 64>(va, v);
; #pragma unroll
;                   for (int dt = 0; dt < 4; ++dt) O[dt] = MFMA32(frag2(v[2 * dt], v[2 * dt + 1]), pf, O[dt]); }
;                 { const bf16x8 pf = pack8(s1, 0); tr8<32 * VST, 8 * VST, 64>(va, v);
; #pragma unroll
;                   for (int dt = 0; dt < 4; ++dt) O[dt] = MFMA32(frag2(v[2 * dt], v[2 * dt + 1]), pf, O[dt]); }
;                 { const bf16x8 pf = pack8(s1, 1); tr8<48 * VST, 8 * VST, 64>(va, v);
; #pragma unroll
;                   for (int dt = 0; dt < 4; ++dt) O[dt] = MFMA32(frag2(v[2 * dt], v[2 * dt + 1]), pf, O[dt]); }
.Lmoba_norsA:
	v_cndmask_b32_e64 v246, v248, v1, s[0:1]
	v_sub_f32_e32 v114, v114, v246
	v_sub_f32_e32 v115, v115, v246
	v_sub_f32_e32 v116, v116, v246
	v_sub_f32_e32 v117, v117, v246
	v_sub_f32_e32 v118, v118, v246
	v_sub_f32_e32 v119, v119, v246
	v_sub_f32_e32 v120, v120, v246
	v_sub_f32_e32 v121, v121, v246
	v_exp_f32_e32 v114, v114
	v_exp_f32_e32 v115, v115
	v_exp_f32_e32 v116, v116
	v_exp_f32_e32 v117, v117
	v_exp_f32_e32 v118, v118
	v_exp_f32_e32 v119, v119
	v_exp_f32_e32 v120, v120
	v_exp_f32_e32 v121, v121
	v_add_f32_e32 v244, v114, v115
	v_add_f32_e32 v245, v116, v117
	v_add_f32_e32 v244, v244, v118
	v_add_f32_e32 v245, v245, v119
	v_add_f32_e32 v244, v244, v120
	v_add_f32_e32 v245, v245, v121
	v_cvt_pk_bf16_f32 v114, v114, v115
	v_cvt_pk_bf16_f32 v115, v116, v117
	v_cvt_pk_bf16_f32 v116, v118, v119
	v_cvt_pk_bf16_f32 v117, v120, v121
	v_sub_f32_e32 v122, v122, v246
	v_sub_f32_e32 v123, v123, v246
	s_waitcnt lgkmcnt(0)
	v_mfma_f32_32x32x16_bf16 v[50:65], v[66:69], v[114:117], v[50:65]
	v_mfma_f32_32x32x16_bf16 v[34:49], v[70:73], v[114:117], v[34:49]
	v_mfma_f32_32x32x16_bf16 v[18:33], v[74:77], v[114:117], v[18:33]
	v_mfma_f32_32x32x16_bf16 v[2:17], v[78:81], v[114:117], v[2:17]
	ds_read_b64_tr_b16 v[66:67], v170 offset:8208
	ds_read_b64_tr_b16 v[68:69], v170 offset:10256
	ds_read_b64_tr_b16 v[70:71], v171 offset:8208
	ds_read_b64_tr_b16 v[72:73], v171 offset:10256
	ds_read_b64_tr_b16 v[74:75], v172 offset:8208
	ds_read_b64_tr_b16 v[76:77], v172 offset:10256
	ds_read_b64_tr_b16 v[78:79], v173 offset:8208
	ds_read_b64_tr_b16 v[80:81], v173 offset:10256
	v_sub_f32_e32 v124, v124, v246
	v_sub_f32_e32 v125, v125, v246
	v_sub_f32_e32 v126, v126, v246
	v_sub_f32_e32 v127, v127, v246
	v_sub_f32_e32 v128, v128, v246
	v_sub_f32_e32 v129, v129, v246
	v_exp_f32_e32 v122, v122
	v_exp_f32_e32 v123, v123
	v_exp_f32_e32 v124, v124
	v_exp_f32_e32 v125, v125
	v_exp_f32_e32 v126, v126
	v_exp_f32_e32 v127, v127
	v_exp_f32_e32 v128, v128
	v_exp_f32_e32 v129, v129
	v_add_f32_e32 v244, v244, v122
	v_add_f32_e32 v245, v245, v123
	v_add_f32_e32 v244, v244, v124
	v_add_f32_e32 v245, v245, v125
	v_add_f32_e32 v244, v244, v126
	v_add_f32_e32 v245, v245, v127
	v_add_f32_e32 v244, v244, v128
	v_add_f32_e32 v245, v245, v129
	v_cvt_pk_bf16_f32 v118, v122, v123
	v_cvt_pk_bf16_f32 v119, v124, v125
	v_cvt_pk_bf16_f32 v120, v126, v127
	v_cvt_pk_bf16_f32 v121, v128, v129
	v_sub_f32_e32 v98, v98, v246
	v_sub_f32_e32 v99, v99, v246
	v_mfma_f32_32x32x16_bf16 v[50:65], v[82:85], v[118:121], v[50:65]
	v_mfma_f32_32x32x16_bf16 v[34:49], v[86:89], v[118:121], v[34:49]
	v_mfma_f32_32x32x16_bf16 v[18:33], v[90:93], v[118:121], v[18:33]
	v_mfma_f32_32x32x16_bf16 v[2:17], v[94:97], v[118:121], v[2:17]
	ds_read_b64_tr_b16 v[82:83], v170 offset:12304
	ds_read_b64_tr_b16 v[84:85], v170 offset:14352
	ds_read_b64_tr_b16 v[86:87], v171 offset:12304
	ds_read_b64_tr_b16 v[88:89], v171 offset:14352
	ds_read_b64_tr_b16 v[90:91], v172 offset:12304
	ds_read_b64_tr_b16 v[92:93], v172 offset:14352
	ds_read_b64_tr_b16 v[94:95], v173 offset:12304
	ds_read_b64_tr_b16 v[96:97], v173 offset:14352
	v_sub_f32_e32 v100, v100, v246
	v_sub_f32_e32 v101, v101, v246
	v_sub_f32_e32 v102, v102, v246
	v_sub_f32_e32 v103, v103, v246
	v_sub_f32_e32 v104, v104, v246
	v_sub_f32_e32 v105, v105, v246
	v_exp_f32_e32 v98, v98
	v_exp_f32_e32 v99, v99
	v_exp_f32_e32 v100, v100
	v_exp_f32_e32 v101, v101
	v_exp_f32_e32 v102, v102
	v_exp_f32_e32 v103, v103
	v_exp_f32_e32 v104, v104
	v_exp_f32_e32 v105, v105
	v_add_f32_e32 v244, v244, v98
	v_add_f32_e32 v245, v245, v99
	v_add_f32_e32 v244, v244, v100
	v_add_f32_e32 v245, v245, v101
	v_add_f32_e32 v244, v244, v102
	v_add_f32_e32 v245, v245, v103
	v_add_f32_e32 v244, v244, v104
	v_add_f32_e32 v245, v245, v105
	v_cvt_pk_bf16_f32 v98, v98, v99
	v_cvt_pk_bf16_f32 v99, v100, v101
	v_cvt_pk_bf16_f32 v100, v102, v103
	v_cvt_pk_bf16_f32 v101, v104, v105
	v_sub_f32_e32 v106, v106, v246
	v_sub_f32_e32 v107, v107, v246
	s_waitcnt lgkmcnt(8)
	v_mfma_f32_32x32x16_bf16 v[50:65], v[66:69], v[98:101], v[50:65]
	v_mfma_f32_32x32x16_bf16 v[34:49], v[70:73], v[98:101], v[34:49]
	v_mfma_f32_32x32x16_bf16 v[18:33], v[74:77], v[98:101], v[18:33]
	v_mfma_f32_32x32x16_bf16 v[2:17], v[78:81], v[98:101], v[2:17]
	v_sub_f32_e32 v108, v108, v246
	v_sub_f32_e32 v109, v109, v246
	v_sub_f32_e32 v110, v110, v246
	v_sub_f32_e32 v111, v111, v246
	v_sub_f32_e32 v112, v112, v246
	v_sub_f32_e32 v113, v113, v246
	v_exp_f32_e32 v106, v106
	v_exp_f32_e32 v107, v107
	v_exp_f32_e32 v108, v108
	v_exp_f32_e32 v109, v109
	v_exp_f32_e32 v110, v110
	v_exp_f32_e32 v111, v111
	v_exp_f32_e32 v112, v112
	v_exp_f32_e32 v113, v113
	v_add_f32_e32 v244, v244, v106
	v_add_f32_e32 v245, v245, v107
	v_add_f32_e32 v244, v244, v108
	v_add_f32_e32 v245, v245, v109
	v_add_f32_e32 v244, v244, v110
	v_add_f32_e32 v245, v245, v111
	v_add_f32_e32 v244, v244, v112
	v_add_f32_e32 v245, v245, v113
	v_cvt_pk_bf16_f32 v102, v106, v107
	v_cvt_pk_bf16_f32 v103, v108, v109
	v_cvt_pk_bf16_f32 v104, v110, v111
	v_cvt_pk_bf16_f32 v105, v112, v113
	v_add_f32_e32 v244, v244, v245
	v_add_f32_e32 v219, v219, v244
	s_waitcnt lgkmcnt(0)
	v_mfma_f32_32x32x16_bf16 v[50:65], v[82:85], v[102:105], v[50:65]
	v_mfma_f32_32x32x16_bf16 v[34:49], v[86:89], v[102:105], v[34:49]
	v_mfma_f32_32x32x16_bf16 v[18:33], v[90:93], v[102:105], v[18:33]
	v_mfma_f32_32x32x16_bf16 v[2:17], v[94:97], v[102:105], v[2:17]
	s_branch .Lmoba_doneA

; #define LAS __attribute__((address_space(3)))
; __device__ __forceinline__ void phase_moba_mfma(const Params& p, LAS unsigned char* lds, unsigned lds_base) {
;     ...
;                 for (int kc = 0; kc < 8; ++kc) { const bf16x8 a0 = *(const LAS bf16x8*)(Ks + 32 * kc), a1 = *(const LAS bf16x8*)(Ks + 32 * KST + 32 * kc);
;                     s0 = MFMA32(a0, qf[kc], s0); s1 = MFMA32(a1, qf[kc], s1); }
;                 const int tq = q0 + i32, kbase = j * 256 + kt * 64;
;                 const bool far = (q0 - (kbase + 63)) >= 790;
;                 const bool diag = own && (kbase + 63 > q0);
;                 const bool lsel = own || ((sel >> j) & 1u);
;                 const int db = tq - kbase - 4 * hh;
;                 if (far) {
; #pragma unroll
;                     for (int r = 0; r < 16; ++r) { s0[r] += c31; s1[r] += c31; }
;                 } else {
;                     const LAS float* bp = (const LAS float*)(lds + OFF_BT) + db;
;                     float b0[16], b1[16];
; #pragma unroll
;                     for (int r = 0; r < 16; ++r) { b0[r] = bp[-(8 * (r >> 2) + (r & 3))]; b1[r] = bp[-(32 + 8 * (r >> 2) + (r & 3))]; }
; #pragma unroll
;                     for (int r = 0; r < 16; ++r) { s0[r] += b0[r]; s1[r] += b1[r]; }
;                 }
;                 if (diag) {
; #pragma unroll
;                     for (int r = 0; r < 16; ++r) { const int d0 = db - (8 * (r >> 2) + (r & 3)); if (d0 < 0) s0[r] = NINF; if (d0 < 32) s1[r] = NINF; }
;                 }
;                 float mx = NINF;
; #pragma unroll
;                 for (int r = 0; r < 16; ++r) { if (!lsel) { s0[r] = NINF; s1[r] = NINF; } mx = fmaxf(mx, fmaxf(s0[r], s1[r])); }
;                 mx = fmaxf(mx, __shfl_xor(mx, 32));
;                 const float mnew = fmaxf(m, mx);
;                 const float alpha = __builtin_amdgcn_exp2f(m - mnew);
;                 float ps = 0.f;
; #pragma unroll
;                 for (int r = 0; r < 16; ++r) { s0[r] = __builtin_amdgcn_exp2f(s0[r] - mnew); s1[r] = __builtin_amdgcn_exp2f(s1[r] - mnew); ps += s0[r] + s1[r]; }
;                 l = l * alpha + ps; m = mnew;
;                 if (__ballot(alpha != 1.0f) != 0ull) {
; #pragma unroll
;                     for (int dt = 0; dt < 4; ++dt)
; #pragma unroll
;                         for (int r = 0; r < 16; ++r) O[dt][r] *= alpha;
;                 }
.Lmoba_tokA:
	ds_read_b128 v[66:69], v162 offset:16
	ds_read_b128 v[70:73], v162 offset:8208
	ds_read_b128 v[74:77], v163 offset:16
	ds_read_b128 v[78:81], v163 offset:8208
	ds_read_b128 v[82:85], v164 offset:16
	ds_read_b128 v[86:89], v164 offset:8208
	ds_read_b128 v[90:93], v165 offset:16
	ds_read_b128 v[94:97], v165 offset:8208
	s_waitcnt lgkmcnt(7)
	v_mfma_f32_32x32x16_bf16 v[114:129], v[66:69], v[130:133], v[228:243]
	ds_read_b128 v[66:69], v166 offset:16
	s_waitcnt lgkmcnt(7)
	v_mfma_f32_32x32x16_bf16 v[98:113], v[70:73], v[130:133], v[228:243]
	ds_read_b128 v[70:73], v166 offset:8208
	s_waitcnt lgkmcnt(7)
	v_mfma_f32_32x32x16_bf16 v[114:129], v[74:77], v[134:137], v[114:129]
	ds_read_b128 v[74:77], v167 offset:16
	s_waitcnt lgkmcnt(7)
	v_mfma_f32_32x32x16_bf16 v[98:113], v[78:81], v[134:137], v[98:113]
	ds_read_b128 v[78:81], v167 offset:8208
	s_waitcnt lgkmcnt(7)
	v_mfma_f32_32x32x16_bf16 v[114:129], v[82:85], v[138:141], v[114:129]
	ds_read_b128 v[82:85], v168 offset:16
	s_waitcnt lgkmcnt(7)
	v_mfma_f32_32x32x16_bf16 v[98:113], v[86:89], v[138:141], v[98:113]
	ds_read_b128 v[86:89], v168 offset:8208
	s_waitcnt lgkmcnt(7)
	v_mfma_f32_32x32x16_bf16 v[114:129], v[90:93], v[142:145], v[114:129]
	ds_read_b128 v[90:93], v169 offset:16
	s_waitcnt lgkmcnt(7)
	v_mfma_f32_32x32x16_bf16 v[98:113], v[94:97], v[142:145], v[98:113]
	ds_read_b128 v[94:97], v169 offset:8208
	s_waitcnt lgkmcnt(7)
	v_mfma_f32_32x32x16_bf16 v[114:129], v[66:69], v[146:149], v[114:129]
	s_waitcnt lgkmcnt(6)
	v_mfma_f32_32x32x16_bf16 v[98:113], v[70:73], v[146:149], v[98:113]
	s_waitcnt lgkmcnt(5)
	v_mfma_f32_32x32x16_bf16 v[114:129], v[74:77], v[150:153], v[114:129]
	s_waitcnt lgkmcnt(4)
	v_mfma_f32_32x32x16_bf16 v[98:113], v[78:81], v[150:153], v[98:113]
	s_waitcnt lgkmcnt(3)
	v_mfma_f32_32x32x16_bf16 v[114:129], v[82:85], v[154:157], v[114:129]
	s_waitcnt lgkmcnt(2)
	v_mfma_f32_32x32x16_bf16 v[98:113], v[86:89], v[154:157], v[98:113]
	s_waitcnt lgkmcnt(1)
	v_mfma_f32_32x32x16_bf16 v[114:129], v[90:93], v[158:161], v[114:129]
	s_waitcnt lgkmcnt(0)
	v_mfma_f32_32x32x16_bf16 v[98:113], v[94:97], v[158:161], v[98:113]
	ds_read_b64_tr_b16 v[66:67], v170 offset:16
	ds_read_b64_tr_b16 v[68:69], v170 offset:2064
	ds_read_b64_tr_b16 v[70:71], v171 offset:16
	ds_read_b64_tr_b16 v[72:73], v171 offset:2064
	ds_read_b64_tr_b16 v[74:75], v172 offset:16
	ds_read_b64_tr_b16 v[76:77], v172 offset:2064
	ds_read_b64_tr_b16 v[78:79], v173 offset:16
	ds_read_b64_tr_b16 v[80:81], v173 offset:2064
	ds_read_b64_tr_b16 v[82:83], v170 offset:4112
	ds_read_b64_tr_b16 v[84:85], v170 offset:6160
	ds_read_b64_tr_b16 v[86:87], v171 offset:4112
	ds_read_b64_tr_b16 v[88:89], v171 offset:6160
	ds_read_b64_tr_b16 v[90:91], v172 offset:4112
	ds_read_b64_tr_b16 v[92:93], v172 offset:6160
	ds_read_b64_tr_b16 v[94:95], v173 offset:4112
	ds_read_b64_tr_b16 v[96:97], v173 offset:6160
	v_max3_f32 v221, v114, v115, v116
	v_max3_f32 v222, v98, v99, v100
	v_max3_f32 v221, v221, v117, v118
	v_max3_f32 v222, v222, v101, v102
	v_max3_f32 v221, v221, v119, v120
	v_max3_f32 v222, v222, v103, v104
	v_max3_f32 v221, v221, v121, v122
	v_max3_f32 v222, v222, v105, v106
	v_max3_f32 v221, v221, v123, v124
	v_max3_f32 v222, v222, v107, v108
	v_max3_f32 v221, v221, v125, v126
	v_max3_f32 v222, v222, v109, v110
	v_max3_f32 v221, v221, v127, v128
	v_max3_f32 v222, v222, v111, v112
	v_max_f32_e32 v221, v221, v129
	v_max_f32_e32 v222, v222, v113
	v_max_f32_e32 v221, v221, v222
	v_mov_b32_e32 v223, v221
	v_mov_b32_e32 v1, v220
	s_nop 1
	v_permlane32_swap_b32_e32 v223, v221
	v_max_f32_e32 v221, v221, v223
	v_cmp_lt_f32_e32 vcc, 0x41000000, v221
	s_cbranch_vccz .Lmoba_ffastA
	v_add_f32_e32 v249, v220, v221
	s_nop 0
	v_cndmask_b32_e32 v1, v220, v249, vcc
	v_sub_f32_e32 v250, v220, v1
	v_sub_f32_e32 v246, v1, v220
	v_exp_f32_e32 v244, v250
	s_and_b32 s2, s2, 0xff
	v_mul_f32_e32 v219, v219, v244
	v_pk_mul_f32 v[2:3], v[2:3], v[244:245] op_sel_hi:[1,0]
	v_pk_mul_f32 v[4:5], v[4:5], v[244:245] op_sel_hi:[1,0]
	v_pk_mul_f32 v[6:7], v[6:7], v[244:245] op_sel_hi:[1,0]
	v_pk_mul_f32 v[8:9], v[8:9], v[244:245] op_sel_hi:[1,0]
	v_pk_mul_f32 v[10:11], v[10:11], v[244:245] op_sel_hi:[1,0]
	v_pk_mul_f32 v[12:13], v[12:13], v[244:245] op_sel_hi:[1,0]
	v_pk_mul_f32 v[14:15], v[14:15], v[244:245] op_sel_hi:[1,0]
	v_pk_mul_f32 v[16:17], v[16:17], v[244:245] op_sel_hi:[1,0]
	v_pk_mul_f32 v[18:19], v[18:19], v[244:245] op_sel_hi:[1,0]
	v_pk_mul_f32 v[20:21], v[20:21], v[244:245] op_sel_hi:[1,0]
	v_pk_mul_f32 v[22:23], v[22:23], v[244:245] op_sel_hi:[1,0]
	v_pk_mul_f32 v[24:25], v[24:25], v[244:245] op_sel_hi:[1,0]
	v_pk_mul_f32 v[26:27], v[26:27], v[244:245] op_sel_hi:[1,0]
	v_pk_mul_f32 v[28:29], v[28:29], v[244:245] op_sel_hi:[1,0]
	v_pk_mul_f32 v[30:31], v[30:31], v[244:245] op_sel_hi:[1,0]
	v_pk_mul_f32 v[32:33], v[32:33], v[244:245] op_sel_hi:[1,0]
	v_pk_mul_f32 v[34:35], v[34:35], v[244:245] op_sel_hi:[1,0]
	v_pk_mul_f32 v[36:37], v[36:37], v[244:245] op_sel_hi:[1,0]
	v_pk_mul_f32 v[38:39], v[38:39], v[244:245] op_sel_hi:[1,0]
	v_pk_mul_f32 v[40:41], v[40:41], v[244:245] op_sel_hi:[1,0]
	v_pk_mul_f32 v[42:43], v[42:43], v[244:245] op_sel_hi:[1,0]
	v_pk_mul_f32 v[44:45], v[44:45], v[244:245] op_sel_hi:[1,0]
	v_pk_mul_f32 v[46:47], v[46:47], v[244:245] op_sel_hi:[1,0]
	v_pk_mul_f32 v[48:49], v[48:49], v[244:245] op_sel_hi:[1,0]
	v_pk_mul_f32 v[50:51], v[50:51], v[244:245] op_sel_hi:[1,0]
	v_pk_mul_f32 v[52:53], v[52:53], v[244:245] op_sel_hi:[1,0]
	v_pk_mul_f32 v[54:55], v[54:55], v[244:245] op_sel_hi:[1,0]
	v_pk_mul_f32 v[56:57], v[56:57], v[244:245] op_sel_hi:[1,0]
	v_pk_mul_f32 v[58:59], v[58:59], v[244:245] op_sel_hi:[1,0]
	v_pk_mul_f32 v[60:61], v[60:61], v[244:245] op_sel_hi:[1,0]
	v_pk_mul_f32 v[62:63], v[62:63], v[244:245] op_sel_hi:[1,0]
	v_pk_mul_f32 v[64:65], v[64:65], v[244:245] op_sel_hi:[1,0]
	v_sub_f32_e32 v114, v114, v246
	v_sub_f32_e32 v98, v98, v246
	v_sub_f32_e32 v115, v115, v246
	v_sub_f32_e32 v99, v99, v246
	v_sub_f32_e32 v116, v116, v246
	v_sub_f32_e32 v100, v100, v246
	v_sub_f32_e32 v117, v117, v246
	v_sub_f32_e32 v101, v101, v246
	v_sub_f32_e32 v118, v118, v246
	v_sub_f32_e32 v102, v102, v246
	v_sub_f32_e32 v119, v119, v246
	v_sub_f32_e32 v103, v103, v246
	v_sub_f32_e32 v120, v120, v246
	v_sub_f32_e32 v104, v104, v246
	v_sub_f32_e32 v121, v121, v246
	v_sub_f32_e32 v105, v105, v246
	v_sub_f32_e32 v122, v122, v246
	v_sub_f32_e32 v106, v106, v246
	v_sub_f32_e32 v123, v123, v246
	v_sub_f32_e32 v107, v107, v246
	v_sub_f32_e32 v124, v124, v246
	v_sub_f32_e32 v108, v108, v246
	v_sub_f32_e32 v125, v125, v246
	v_sub_f32_e32 v109, v109, v246
	v_sub_f32_e32 v126, v126, v246
	v_sub_f32_e32 v110, v110, v246
	v_sub_f32_e32 v127, v127, v246
	v_sub_f32_e32 v111, v111, v246
	v_sub_f32_e32 v128, v128, v246
	v_sub_f32_e32 v112, v112, v246
	v_sub_f32_e32 v129, v129, v246
	v_sub_f32_e32 v113, v113, v246
; #define MFMA32(a, b, c) __builtin_amdgcn_mfma_f32_32x32x16_bf16((a), (b), (c), 0, 0, 0)
; __device__ __forceinline__ void phase_moba_mfma(const Params& p, LAS unsigned char* lds, unsigned lds_base) {
;     ...
;                 for (int r = 0; r < 16; ++r) { s0[r] = __builtin_amdgcn_exp2f(s0[r] - mnew); s1[r] = __builtin_amdgcn_exp2f(s1[r] - mnew); ps += s0[r] + s1[r]; }
;                 l = l * alpha + ps; m = mnew;
;                 if (__ballot(alpha != 1.0f) != 0ull) {
; #pragma unroll
;                     for (int dt = 0; dt < 4; ++dt)
; #pragma unroll
;                         for (int r = 0; r < 16; ++r) O[dt][r] *= alpha;
;                 }
;                 const unsigned va = vbase + buf * 64 * VST;
;                 u32x2 v[8];
;                 { const bf16x8 pf = pack8(s0, 0); tr8<0, 8 * VST, 64>(va, v);
; #pragma unroll
;                   for (int dt = 0; dt < 4; ++dt) O[dt] = MFMA32(frag2(v[2 * dt], v[2 * dt + 1]), pf, O[dt]); }
;                 { const bf16x8 pf = pack8(s0, 1); tr8<16 * VST, 8 * VST, 64>(va, v);
; #pragma unroll
;                   for (int dt = 0; dt < 4; ++dt) O[dt] = MFMA32(frag2(v[2 * dt], v[2 * dt + 1]), pf, O[dt]); }
;                 { const bf16x8 pf = pack8(s1, 0); tr8<32 * VST, 8 * VST, 64>(va, v);
; #pragma unroll
;                   for (int dt = 0; dt < 4; ++dt) O[dt] = MFMA32(frag2(v[2 * dt], v[2 * dt + 1]), pf, O[dt]); }
;                 { const bf16x8 pf = pack8(s1, 1); tr8<48 * VST, 8 * VST, 64>(va, v);
; #pragma unroll
;                   for (int dt = 0; dt < 4; ++dt) O[dt] = MFMA32(frag2(v[2 * dt], v[2 * dt + 1]), pf, O[dt]); }
.Lmoba_ffastA:
	v_exp_f32_e32 v114, v114
	v_exp_f32_e32 v115, v115
	v_exp_f32_e32 v116, v116
	v_exp_f32_e32 v117, v117
	v_exp_f32_e32 v118, v118
	v_exp_f32_e32 v119, v119
	v_exp_f32_e32 v120, v120
	v_exp_f32_e32 v121, v121
	v_add_f32_e32 v244, v114, v115
	v_add_f32_e32 v245, v116, v117
	v_add_f32_e32 v244, v244, v118
	v_add_f32_e32 v245, v245, v119
	v_add_f32_e32 v244, v244, v120
	v_add_f32_e32 v245, v245, v121
	v_cvt_pk_bf16_f32 v114, v114, v115
	v_cvt_pk_bf16_f32 v115, v116, v117
	v_cvt_pk_bf16_f32 v116, v118, v119
	v_cvt_pk_bf16_f32 v117, v120, v121
	v_exp_f32_e32 v122, v122
	v_exp_f32_e32 v123, v123
	s_waitcnt lgkmcnt(0)
	v_mfma_f32_32x32x16_bf16 v[50:65], v[66:69], v[114:117], v[50:65]
	v_mfma_f32_32x32x16_bf16 v[34:49], v[70:73], v[114:117], v[34:49]
	v_mfma_f32_32x32x16_bf16 v[18:33], v[74:77], v[114:117], v[18:33]
	v_mfma_f32_32x32x16_bf16 v[2:17], v[78:81], v[114:117], v[2:17]
	ds_read_b64_tr_b16 v[66:67], v170 offset:8208
	ds_read_b64_tr_b16 v[68:69], v170 offset:10256
	ds_read_b64_tr_b16 v[70:71], v171 offset:8208
	ds_read_b64_tr_b16 v[72:73], v171 offset:10256
	ds_read_b64_tr_b16 v[74:75], v172 offset:8208
	ds_read_b64_tr_b16 v[76:77], v172 offset:10256
	ds_read_b64_tr_b16 v[78:79], v173 offset:8208
	ds_read_b64_tr_b16 v[80:81], v173 offset:10256
	v_exp_f32_e32 v124, v124
	v_exp_f32_e32 v125, v125
	v_exp_f32_e32 v126, v126
	v_exp_f32_e32 v127, v127
	v_exp_f32_e32 v128, v128
	v_exp_f32_e32 v129, v129
	v_add_f32_e32 v244, v244, v122
	v_add_f32_e32 v245, v245, v123
	v_add_f32_e32 v244, v244, v124
	v_add_f32_e32 v245, v245, v125
	v_add_f32_e32 v244, v244, v126
	v_add_f32_e32 v245, v245, v127
	v_add_f32_e32 v244, v244, v128
	v_add_f32_e32 v245, v245, v129
	v_cvt_pk_bf16_f32 v118, v122, v123
	v_cvt_pk_bf16_f32 v119, v124, v125
	v_cvt_pk_bf16_f32 v120, v126, v127
	v_cvt_pk_bf16_f32 v121, v128, v129
	v_exp_f32_e32 v98, v98
	v_exp_f32_e32 v99, v99
	v_mfma_f32_32x32x16_bf16 v[50:65], v[82:85], v[118:121], v[50:65]
	v_mfma_f32_32x32x16_bf16 v[34:49], v[86:89], v[118:121], v[34:49]
	v_mfma_f32_32x32x16_bf16 v[18:33], v[90:93], v[118:121], v[18:33]
	v_mfma_f32_32x32x16_bf16 v[2:17], v[94:97], v[118:121], v[2:17]
	ds_read_b64_tr_b16 v[82:83], v170 offset:12304
	ds_read_b64_tr_b16 v[84:85], v170 offset:14352
	ds_read_b64_tr_b16 v[86:87], v171 offset:12304
	ds_read_b64_tr_b16 v[88:89], v171 offset:14352
	ds_read_b64_tr_b16 v[90:91], v172 offset:12304
	ds_read_b64_tr_b16 v[92:93], v172 offset:14352
	ds_read_b64_tr_b16 v[94:95], v173 offset:12304
	ds_read_b64_tr_b16 v[96:97], v173 offset:14352
	v_exp_f32_e32 v100, v100
	v_exp_f32_e32 v101, v101
	v_exp_f32_e32 v102, v102
	v_exp_f32_e32 v103, v103
	v_exp_f32_e32 v104, v104
	v_exp_f32_e32 v105, v105
	v_add_f32_e32 v244, v244, v98
	v_add_f32_e32 v245, v245, v99
	v_add_f32_e32 v244, v244, v100
	v_add_f32_e32 v245, v245, v101
	v_add_f32_e32 v244, v244, v102
	v_add_f32_e32 v245, v245, v103
	v_add_f32_e32 v244, v244, v104
	v_add_f32_e32 v245, v245, v105
	v_cvt_pk_bf16_f32 v98, v98, v99
	v_cvt_pk_bf16_f32 v99, v100, v101
	v_cvt_pk_bf16_f32 v100, v102, v103
	v_cvt_pk_bf16_f32 v101, v104, v105
	v_exp_f32_e32 v106, v106
	v_exp_f32_e32 v107, v107
	s_waitcnt lgkmcnt(8)
	v_mfma_f32_32x32x16_bf16 v[50:65], v[66:69], v[98:101], v[50:65]
	v_mfma_f32_32x32x16_bf16 v[34:49], v[70:73], v[98:101], v[34:49]
	v_mfma_f32_32x32x16_bf16 v[18:33], v[74:77], v[98:101], v[18:33]
	v_mfma_f32_32x32x16_bf16 v[2:17], v[78:81], v[98:101], v[2:17]
	v_exp_f32_e32 v108, v108
	v_exp_f32_e32 v109, v109
	v_exp_f32_e32 v110, v110
	v_exp_f32_e32 v111, v111
	v_exp_f32_e32 v112, v112
	v_exp_f32_e32 v113, v113
	v_add_f32_e32 v244, v244, v106
	v_add_f32_e32 v245, v245, v107
	v_add_f32_e32 v244, v244, v108
	v_add_f32_e32 v245, v245, v109
	v_add_f32_e32 v244, v244, v110
	v_add_f32_e32 v245, v245, v111
	v_add_f32_e32 v244, v244, v112
	v_add_f32_e32 v245, v245, v113
	v_cvt_pk_bf16_f32 v102, v106, v107
	v_cvt_pk_bf16_f32 v103, v108, v109
	v_cvt_pk_bf16_f32 v104, v110, v111
	v_cvt_pk_bf16_f32 v105, v112, v113
	v_add_f32_e32 v244, v244, v245
	v_add_f32_e32 v219, v219, v244
	s_waitcnt lgkmcnt(0)
	v_mfma_f32_32x32x16_bf16 v[50:65], v[82:85], v[102:105], v[50:65]
	v_mfma_f32_32x32x16_bf16 v[34:49], v[86:89], v[102:105], v[34:49]
	v_mfma_f32_32x32x16_bf16 v[18:33], v[90:93], v[102:105], v[18:33]
	v_mfma_f32_32x32x16_bf16 v[2:17], v[94:97], v[102:105], v[2:17]
.Lmoba_doneA:
.Lmoba_tail:
	s_andn2_b64 vcc, exec, s[14:15]
	s_cbranch_vccz .LBB0_759
	s_branch .LBB0_760

; #define MOBA_LOAD(jj, kk) do { const size_t r_ = (rowb + (jj) * 256 + (kk) * 64 + lrow) * D_ + h * 128 + lc * 16; rk0 = *(const u32x4*)(MBK + r_); rk1 = *(const u32x4*)(MBK + r_ + 8); rv0 = *(const u32x4*)(MBV + r_); rv1 = *(const u32x4*)(MBV + r_ + 8); } while (0)
; #define MOBA_STORE(bb) do { LAS unsigned char* kd = lds + OFF_K + (bb) * 64 * KST + lrow * KST + lc * 32; *(LAS u32x4*)kd = rk0; *(LAS u32x4*)(kd + 16) = rk1; \
;         LAS unsigned char* vd = lds + OFF_V + (bb) * 64 * VST + lrow * VST + lc * 32; *(LAS u32x4*)vd = rv0; *(LAS u32x4*)(vd + 16) = rv1; } while (0)
; __device__ __forceinline__ void phase_moba_mfma(const Params& p, LAS unsigned char* lds, unsigned lds_base) {
;     ...
;         while (j >= 0) {
;             int nj = j, nkt = kt + 1;
;     ...
;             if (nj >= 0) MOBA_LOAD(nj, nkt);
;     ...
;             if (nj >= 0) MOBA_STORE(buf ^ 1);
;             __syncthreads();
;             j = nj; kt = nkt; buf ^= 1;
;         }
.LBB0_758:
	v_mov_b32_e32 v1, v220
	s_bitcmp0_b32 s2, 0
	s_cbranch_scc1 .Lmoba_ret1
	s_add_i32 s0, s100, 3
	s_and_b32 s0, s0, 3
	s_mov_b32 s45, 1
	s_branch .Lmoba_pvblk

; __device__ __forceinline__ void phase_moba_mfma(const Params& p, LAS unsigned char* lds, unsigned lds_base) {
;     ...
;         l += __shfl_xor(l, 32);
;         const float inv = 1.0f / l;
.Lmoba_exit:
	s_bitcmp0_b32 s2, 0
	s_cbranch_scc1 .LBB0_734
	s_mov_b32 s0, s100
	s_mov_b32 s45, 2
	s_branch .Lmoba_pvblk
